# P0 bulk bf16 output stores also marked nt, on top of the P0 nt-loads version
# baseline (speedup 1.0000x reference)
; #define GAS __attribute__((address_space(1)))
; #define LAS __attribute__((address_space(3)))
; #define LDS_WAIT() asm volatile("s_waitcnt lgkmcnt(0)" ::: "memory")
; __device__ __forceinline__ unsigned pk2(float lo, float hi) { return f2bf(lo) | (f2bf(hi) << 16); }
; __device__ __forceinline__ void p0_item_store(const P0Item& I, const float (&wv)[32], LAS float* scr, int lane) {
; #pragma unroll
;     for (int i = 0; i < 8; ++i) { const int kk = 8 * i + (lane >> 3); const float s = I.scale ? I.scale[I.k0 + kk] : 1.f; LAS float* d = scr + kk * 33 + 4 * (lane & 7);
;         d[0] = wv[4 * i] * s; d[1] = wv[4 * i + 1] * s; d[2] = wv[4 * i + 2] * s; d[3] = wv[4 * i + 3] * s; }
;     LDS_WAIT(); asm volatile("" ::: "memory");
;     const int c = lane & 7;
; #pragma unroll
;     for (int j = 0; j < 4; ++j) { const int n = (lane >> 3) + 8 * j; const int ns = I.perm ? rope_perm(n) : n; const LAS float* s = scr + (8 * c) * 33 + ns;
;         v4u o; o.x = pk2(s[0 * 33], s[1 * 33]); o.y = pk2(s[2 * 33], s[3 * 33]); o.z = pk2(s[4 * 33], s[5 * 33]); o.w = pk2(s[6 * 33], s[7 * 33]);
;         *(GAS v4u*)(I.WT + (size_t)(I.out_row0 + n) * I.K + I.k0 + 8 * c) = o; }
;     LDS_WAIT(); asm volatile("" ::: "memory");
; }
.LBB0_47:
	s_waitcnt vmcnt(0)
	v_pk_mul_f32 v[96:97], v[96:97], v[104:105] op_sel_hi:[1,0]
	ds_write2_b32 v139, v96, v97 offset1:1
	v_pk_mul_f32 v[96:97], v[98:99], v[104:105] op_sel_hi:[1,0]
	ds_write2_b32 v140, v96, v97 offset1:1
	s_and_b64 vcc, s[0:1], s[84:85]
	s_waitcnt lgkmcnt(0)
	v_cndmask_b32_e32 v96, v132, v154, vcc
	v_lshl_add_u32 v102, v96, 2, v153
	ds_read2_b32 v[96:97], v102 offset1:33
	s_and_b64 vcc, s[2:3], s[84:85]
	s_lshl_b64 s[8:9], s[86:87], 1
	s_waitcnt lgkmcnt(0)
	v_bfe_u32 v98, v96, 16, 1
	v_add3_u32 v96, v96, v98, s62
	ds_read2_b32 v[98:99], v102 offset0:66 offset1:99
	v_bfe_u32 v100, v97, 16, 1
	v_add3_u32 v97, v97, v100, s62
	ds_read2_b32 v[100:101], v102 offset0:132 offset1:165
	v_lshrrev_b32_e32 v96, 16, v96
	v_and_or_b32 v96, v97, s63, v96
	s_waitcnt lgkmcnt(1)
	v_bfe_u32 v97, v98, 16, 1
	v_add3_u32 v97, v98, v97, s62
	v_bfe_u32 v98, v99, 16, 1
	ds_read2_b32 v[102:103], v102 offset0:198 offset1:231
	v_lshrrev_b32_e32 v97, 16, v97
	v_add3_u32 v98, v99, v98, s62
	v_and_or_b32 v97, v98, s63, v97
	s_waitcnt lgkmcnt(1)
	v_bfe_u32 v98, v100, 16, 1
	v_add3_u32 v98, v100, v98, s62
	v_bfe_u32 v99, v101, 16, 1
	v_lshrrev_b32_e32 v98, 16, v98
	v_add3_u32 v99, v101, v99, s62
	v_and_or_b32 v98, v99, s63, v98
	s_waitcnt lgkmcnt(0)
	v_bfe_u32 v99, v102, 16, 1
	v_add3_u32 v99, v102, v99, s62
	v_bfe_u32 v100, v103, 16, 1
	v_lshrrev_b32_e32 v99, 16, v99
	v_add3_u32 v100, v103, v100, s62
	v_and_or_b32 v99, v100, s63, v99
	v_add_u32_e32 v100, s94, v132
	v_ashrrev_i32_e32 v101, 31, v100
	v_cndmask_b32_e32 v102, v149, v155, vcc
	v_lshlrev_b64 v[100:101], 11, v[100:101]
	v_lshl_add_u32 v104, v102, 2, v153
	v_lshl_add_u64 v[100:101], s[78:79], 0, v[100:101]
	ds_read2_b32 v[102:103], v104 offset1:33
	v_lshl_add_u64 v[100:101], v[100:101], 0, s[8:9]
	v_lshl_add_u64 v[100:101], v[100:101], 0, v[134:135]
	global_store_dwordx4 v[100:101], v[96:99], off nt
	ds_read2_b32 v[98:99], v104 offset0:66 offset1:99
	ds_read2_b32 v[100:101], v104 offset0:132 offset1:165
	s_waitcnt lgkmcnt(2)
	v_bfe_u32 v96, v102, 16, 1
	v_add3_u32 v96, v102, v96, s62
	v_bfe_u32 v97, v103, 16, 1
	v_lshrrev_b32_e32 v96, 16, v96
	v_add3_u32 v97, v103, v97, s62
	v_and_or_b32 v96, v97, s63, v96
	s_waitcnt lgkmcnt(1)
	v_bfe_u32 v97, v98, 16, 1
	v_add3_u32 v97, v98, v97, s62
	v_bfe_u32 v98, v99, 16, 1
	ds_read2_b32 v[102:103], v104 offset0:198 offset1:231
	v_lshrrev_b32_e32 v97, 16, v97
	v_add3_u32 v98, v99, v98, s62
	v_and_or_b32 v97, v98, s63, v97
	s_waitcnt lgkmcnt(1)
	v_bfe_u32 v98, v100, 16, 1
	v_add3_u32 v98, v100, v98, s62
	v_bfe_u32 v99, v101, 16, 1
	v_lshrrev_b32_e32 v98, 16, v98
	v_add3_u32 v99, v101, v99, s62
	v_and_or_b32 v98, v99, s63, v98
	s_waitcnt lgkmcnt(0)
	v_bfe_u32 v99, v102, 16, 1
	v_add3_u32 v99, v102, v99, s62
	v_bfe_u32 v100, v103, 16, 1
	v_lshrrev_b32_e32 v99, 16, v99
	v_add3_u32 v100, v103, v100, s62
	v_and_or_b32 v99, v100, s63, v99
	v_add_u32_e32 v100, s94, v149
	s_and_b64 vcc, s[4:5], s[84:85]
	v_ashrrev_i32_e32 v101, 31, v100
	v_cndmask_b32_e32 v102, v151, v156, vcc
	v_lshlrev_b64 v[100:101], 11, v[100:101]
	v_lshl_add_u32 v104, v102, 2, v153
	ds_read2_b32 v[102:103], v104 offset1:33
	v_lshl_add_u64 v[100:101], s[78:79], 0, v[100:101]
	v_lshl_add_u64 v[100:101], v[100:101], 0, s[8:9]
	v_lshl_add_u64 v[100:101], v[100:101], 0, v[134:135]
	global_store_dwordx4 v[100:101], v[96:99], off nt
	ds_read2_b32 v[98:99], v104 offset0:66 offset1:99
	ds_read2_b32 v[100:101], v104 offset0:132 offset1:165
	s_waitcnt lgkmcnt(2)
	v_bfe_u32 v96, v102, 16, 1
	v_add3_u32 v96, v102, v96, s62
	v_bfe_u32 v97, v103, 16, 1
	v_lshrrev_b32_e32 v96, 16, v96
	v_add3_u32 v97, v103, v97, s62
	v_and_or_b32 v96, v97, s63, v96
	s_waitcnt lgkmcnt(1)
	v_bfe_u32 v97, v98, 16, 1
	v_add3_u32 v97, v98, v97, s62
	v_bfe_u32 v98, v99, 16, 1
	ds_read2_b32 v[102:103], v104 offset0:198 offset1:231
	v_lshrrev_b32_e32 v97, 16, v97
	v_add3_u32 v98, v99, v98, s62
	v_and_or_b32 v97, v98, s63, v97
	s_waitcnt lgkmcnt(1)
	v_bfe_u32 v98, v100, 16, 1
	v_add3_u32 v98, v100, v98, s62
	v_bfe_u32 v99, v101, 16, 1
	v_lshrrev_b32_e32 v98, 16, v98
	v_add3_u32 v99, v101, v99, s62
	v_and_or_b32 v98, v99, s63, v98
	s_waitcnt lgkmcnt(0)
	v_bfe_u32 v99, v102, 16, 1
	v_add3_u32 v99, v102, v99, s62
	v_bfe_u32 v100, v103, 16, 1
	v_lshrrev_b32_e32 v99, 16, v99
	v_add3_u32 v100, v103, v100, s62
	v_and_or_b32 v99, v100, s63, v99
	v_add_u32_e32 v100, s94, v151
	s_and_b64 vcc, s[6:7], s[84:85]
	v_ashrrev_i32_e32 v101, 31, v100
	v_cndmask_b32_e32 v102, v152, v157, vcc
	v_lshlrev_b64 v[100:101], 11, v[100:101]
	v_lshl_add_u32 v104, v102, 2, v153
	ds_read2_b32 v[102:103], v104 offset1:33
	v_lshl_add_u64 v[100:101], s[78:79], 0, v[100:101]
	v_lshl_add_u64 v[100:101], v[100:101], 0, s[8:9]
	v_lshl_add_u64 v[100:101], v[100:101], 0, v[134:135]
	global_store_dwordx4 v[100:101], v[96:99], off nt
	ds_read2_b32 v[98:99], v104 offset0:66 offset1:99
	ds_read2_b32 v[100:101], v104 offset0:132 offset1:165
	s_waitcnt lgkmcnt(2)
	v_bfe_u32 v96, v102, 16, 1
	v_add3_u32 v96, v102, v96, s62
	v_bfe_u32 v97, v103, 16, 1
	v_lshrrev_b32_e32 v96, 16, v96
	v_add3_u32 v97, v103, v97, s62
	v_and_or_b32 v96, v97, s63, v96
	s_waitcnt lgkmcnt(1)
	v_bfe_u32 v97, v98, 16, 1
	v_add3_u32 v97, v98, v97, s62
	v_bfe_u32 v98, v99, 16, 1
	ds_read2_b32 v[102:103], v104 offset0:198 offset1:231
	v_lshrrev_b32_e32 v97, 16, v97
	v_add3_u32 v98, v99, v98, s62
	v_and_or_b32 v97, v98, s63, v97
	s_waitcnt lgkmcnt(1)
	v_bfe_u32 v98, v100, 16, 1
	v_add3_u32 v98, v100, v98, s62
	v_bfe_u32 v99, v101, 16, 1
	v_lshrrev_b32_e32 v98, 16, v98
	v_add3_u32 v99, v101, v99, s62
	v_and_or_b32 v98, v99, s63, v98
	s_waitcnt lgkmcnt(0)
	v_bfe_u32 v99, v102, 16, 1
	v_add3_u32 v99, v102, v99, s62
	v_bfe_u32 v100, v103, 16, 1
	v_lshrrev_b32_e32 v99, 16, v99
	v_add3_u32 v100, v103, v100, s62
	v_and_or_b32 v99, v100, s63, v99
	v_add_u32_e32 v100, s94, v152
	v_ashrrev_i32_e32 v101, 31, v100
	v_lshlrev_b64 v[100:101], 11, v[100:101]
	v_lshl_add_u64 v[100:101], s[78:79], 0, v[100:101]
	v_lshl_add_u64 v[100:101], v[100:101], 0, s[8:9]
	v_lshl_add_u64 v[100:101], v[100:101], 0, v[134:135]
	global_store_dwordx4 v[100:101], v[96:99], off nt
	s_waitcnt lgkmcnt(0)

; #define GAS __attribute__((address_space(1)))
; #define LAS __attribute__((address_space(3)))
; #define LDS_WAIT() asm volatile("s_waitcnt lgkmcnt(0)" ::: "memory")
; __device__ __forceinline__ unsigned pk2(float lo, float hi) { return f2bf(lo) | (f2bf(hi) << 16); }
; __device__ __forceinline__ void p0_item_store(const P0Item& I, const float (&wv)[32], LAS float* scr, int lane) {
; #pragma unroll
;     for (int i = 0; i < 8; ++i) { const int kk = 8 * i + (lane >> 3); const float s = I.scale ? I.scale[I.k0 + kk] : 1.f; LAS float* d = scr + kk * 33 + 4 * (lane & 7);
;         d[0] = wv[4 * i] * s; d[1] = wv[4 * i + 1] * s; d[2] = wv[4 * i + 2] * s; d[3] = wv[4 * i + 3] * s; }
;     LDS_WAIT(); asm volatile("" ::: "memory");
;     const int c = lane & 7;
; #pragma unroll
;     for (int j = 0; j < 4; ++j) { const int n = (lane >> 3) + 8 * j; const int ns = I.perm ? rope_perm(n) : n; const LAS float* s = scr + (8 * c) * 33 + ns;
;         v4u o; o.x = pk2(s[0 * 33], s[1 * 33]); o.y = pk2(s[2 * 33], s[3 * 33]); o.z = pk2(s[4 * 33], s[5 * 33]); o.w = pk2(s[6 * 33], s[7 * 33]);
;         *(GAS v4u*)(I.WT + (size_t)(I.out_row0 + n) * I.K + I.k0 + 8 * c) = o; }
;     LDS_WAIT(); asm volatile("" ::: "memory");
; }
; __device__ __forceinline__ void p0_prologue(Frame& F, const Ptrs& P) {
;     ...
;         for (int it = gw; it < NITEMS; it += 3 * NGW) {
;             const bool h1 = it + NGW < NITEMS, h2 = it + 2 * NGW < NITEMS;
;             P0_DECODE(Ia, it); p0_item_load(Ia, wa, lane);
;             if (h1) { P0_DECODE(Ib, it + NGW); p0_item_load(Ib, wb, lane); }
;             p0_item_store(Ia, wa, scr, lane);
;             if (h2) { P0_DECODE(Ia, it + 2 * NGW); p0_item_load(Ia, wa, lane); }
;             if (h1) p0_item_store(Ib, wb, scr, lane);
;             if (h2) p0_item_store(Ia, wa, scr, lane);
.LBB0_83:
	v_add_u32_e32 v162, 0xc60, v159
	ds_write2_b32 v162, v142, v143 offset1:1
	v_add_u32_e32 v142, 0xc68, v159
	s_add_i32 s95, s13, s64
	ds_write2_b32 v142, v144, v145 offset1:1
	s_waitcnt vmcnt(0)
	v_pk_mul_f32 v[144:145], v[96:97], v[140:141] op_sel_hi:[1,0]
	v_add_u32_e32 v139, 0x1080, v159
	s_cmpk_lt_i32 s95, 0xa10
	ds_write2_b32 v139, v144, v145 offset1:1
	v_pk_mul_f32 v[144:145], v[98:99], v[140:141] op_sel_hi:[1,0]
	v_add_u32_e32 v140, 0x1088, v159
	s_cselect_b64 s[88:89], -1, 0
	ds_write2_b32 v140, v144, v145 offset1:1
	s_and_b64 vcc, s[0:1], s[84:85]
	s_waitcnt lgkmcnt(0)
	v_cndmask_b32_e32 v138, v132, v154, vcc
	v_lshl_add_u32 v138, v138, 2, v153
	ds_read2_b32 v[144:145], v138 offset1:33
	ds_read2_b32 v[166:167], v138 offset0:66 offset1:99
	ds_read2_b32 v[168:169], v138 offset0:198 offset1:231
	s_add_i32 s83, s34, s83
	s_and_b64 s[14:15], s[2:3], s[84:85]
	s_waitcnt lgkmcnt(2)
	v_bfe_u32 v143, v144, 16, 1
	v_add3_u32 v143, v144, v143, s62
	v_bfe_u32 v144, v145, 16, 1
	v_lshrrev_b32_e32 v143, 16, v143
	v_add3_u32 v144, v145, v144, s62
	v_and_or_b32 v164, v144, s63, v143
	ds_read2_b32 v[144:145], v138 offset0:132 offset1:165
	s_waitcnt lgkmcnt(2)
	v_bfe_u32 v143, v166, 16, 1
	v_add3_u32 v143, v166, v143, s62
	v_bfe_u32 v165, v167, 16, 1
	v_lshrrev_b32_e32 v143, 16, v143
	v_add3_u32 v165, v167, v165, s62
	v_and_or_b32 v165, v165, s63, v143
	s_waitcnt lgkmcnt(0)
	v_bfe_u32 v143, v144, 16, 1
	v_add3_u32 v143, v144, v143, s62
	v_lshrrev_b32_e32 v138, 16, v143
	v_bfe_u32 v143, v145, 16, 1
	v_add3_u32 v143, v145, v143, s62
	v_and_or_b32 v166, v143, s63, v138
	v_bfe_u32 v138, v168, 16, 1
	v_add3_u32 v138, v168, v138, s62
	v_bfe_u32 v143, v169, 16, 1
	v_lshrrev_b32_e32 v138, 16, v138
	v_add3_u32 v143, v169, v143, s62
	v_add_u32_e32 v144, s83, v132
	v_and_or_b32 v167, v143, s63, v138
	v_ashrrev_i32_e32 v145, 31, v144
	v_cndmask_b32_e64 v138, v149, v155, s[14:15]
	s_ashr_i32 s87, s86, 31
	v_lshlrev_b64 v[168:169], 11, v[144:145]
	v_lshl_add_u32 v138, v138, 2, v153
	s_lshl_b64 s[92:93], s[86:87], 1
	ds_read2_b32 v[170:171], v138 offset1:33
	v_lshl_add_u64 v[168:169], s[78:79], 0, v[168:169]
	v_lshl_add_u64 v[168:169], v[168:169], 0, s[92:93]
	v_lshl_add_u64 v[168:169], v[168:169], 0, v[134:135]
	global_store_dwordx4 v[168:169], v[164:167], off nt
	ds_read2_b32 v[166:167], v138 offset0:66 offset1:99
	s_waitcnt lgkmcnt(1)
	v_bfe_u32 v143, v170, 16, 1
	v_add3_u32 v143, v170, v143, s62
	v_bfe_u32 v145, v171, 16, 1
	ds_read2_b32 v[168:169], v138 offset0:132 offset1:165
	v_lshrrev_b32_e32 v143, 16, v143
	v_add3_u32 v145, v171, v145, s62
	v_and_or_b32 v164, v145, s63, v143
	s_waitcnt lgkmcnt(1)
	v_bfe_u32 v143, v166, 16, 1
	v_add3_u32 v143, v166, v143, s62
	v_bfe_u32 v145, v167, 16, 1
	v_lshrrev_b32_e32 v143, 16, v143
	v_add3_u32 v145, v167, v145, s62
	ds_read2_b32 v[170:171], v138 offset0:198 offset1:231
	v_and_or_b32 v165, v145, s63, v143
	s_waitcnt lgkmcnt(1)
	v_bfe_u32 v143, v168, 16, 1
	v_add3_u32 v143, v168, v143, s62
	v_lshrrev_b32_e32 v138, 16, v143
	v_bfe_u32 v143, v169, 16, 1
	v_add3_u32 v143, v169, v143, s62
	v_and_or_b32 v166, v143, s63, v138
	s_waitcnt lgkmcnt(0)
	v_bfe_u32 v138, v170, 16, 1
	v_add3_u32 v138, v170, v138, s62
	v_bfe_u32 v143, v171, 16, 1
	s_and_b64 s[10:11], s[4:5], s[84:85]
	v_lshrrev_b32_e32 v138, 16, v138
	v_add3_u32 v143, v171, v143, s62
	v_add_u32_e32 v168, 8, v144
	v_and_or_b32 v167, v143, s63, v138
	v_ashrrev_i32_e32 v169, 31, v168
	v_cndmask_b32_e64 v138, v151, v156, s[10:11]
	v_lshlrev_b64 v[168:169], 11, v[168:169]
	v_lshl_add_u32 v138, v138, 2, v153
	ds_read2_b32 v[170:171], v138 offset1:33
	v_lshl_add_u64 v[168:169], s[78:79], 0, v[168:169]
	v_lshl_add_u64 v[168:169], v[168:169], 0, s[92:93]
	v_lshl_add_u64 v[168:169], v[168:169], 0, v[134:135]
	global_store_dwordx4 v[168:169], v[164:167], off nt
	ds_read2_b32 v[166:167], v138 offset0:66 offset1:99
	s_waitcnt lgkmcnt(1)
	v_bfe_u32 v143, v170, 16, 1
	v_add3_u32 v143, v170, v143, s62
	v_bfe_u32 v145, v171, 16, 1
	ds_read2_b32 v[168:169], v138 offset0:132 offset1:165
	v_lshrrev_b32_e32 v143, 16, v143
	v_add3_u32 v145, v171, v145, s62
	v_and_or_b32 v164, v145, s63, v143
	s_waitcnt lgkmcnt(1)
	v_bfe_u32 v143, v166, 16, 1
	v_add3_u32 v143, v166, v143, s62
	v_bfe_u32 v145, v167, 16, 1
	v_lshrrev_b32_e32 v143, 16, v143
	v_add3_u32 v145, v167, v145, s62
	ds_read2_b32 v[170:171], v138 offset0:198 offset1:231
	v_and_or_b32 v165, v145, s63, v143
	s_waitcnt lgkmcnt(1)
	v_bfe_u32 v143, v168, 16, 1
	v_add3_u32 v143, v168, v143, s62
	v_lshrrev_b32_e32 v138, 16, v143
	v_bfe_u32 v143, v169, 16, 1
	v_add3_u32 v143, v169, v143, s62
	v_and_or_b32 v166, v143, s63, v138
	s_waitcnt lgkmcnt(0)
	v_bfe_u32 v138, v170, 16, 1
	v_add3_u32 v138, v170, v138, s62
	v_bfe_u32 v143, v171, 16, 1
	s_and_b64 vcc, s[6:7], s[84:85]
	v_lshrrev_b32_e32 v138, 16, v138
	v_add3_u32 v143, v171, v143, s62
	v_add_u32_e32 v168, 16, v144
	v_and_or_b32 v167, v143, s63, v138
	v_ashrrev_i32_e32 v169, 31, v168
	v_cndmask_b32_e32 v138, v152, v157, vcc
	v_lshlrev_b64 v[168:169], 11, v[168:169]
	v_lshl_add_u32 v138, v138, 2, v153
	ds_read2_b32 v[170:171], v138 offset1:33
	v_lshl_add_u64 v[168:169], s[78:79], 0, v[168:169]
	v_lshl_add_u64 v[168:169], v[168:169], 0, s[92:93]
	v_lshl_add_u64 v[168:169], v[168:169], 0, v[134:135]
	global_store_dwordx4 v[168:169], v[164:167], off nt
	ds_read2_b32 v[166:167], v138 offset0:66 offset1:99
	s_waitcnt lgkmcnt(1)
	v_bfe_u32 v143, v170, 16, 1
	v_add3_u32 v143, v170, v143, s62
	v_bfe_u32 v145, v171, 16, 1
	ds_read2_b32 v[168:169], v138 offset0:132 offset1:165
	v_lshrrev_b32_e32 v143, 16, v143
	v_add3_u32 v145, v171, v145, s62
	v_and_or_b32 v164, v145, s63, v143
	s_waitcnt lgkmcnt(1)
	v_bfe_u32 v143, v166, 16, 1
	v_add3_u32 v143, v166, v143, s62
	v_bfe_u32 v145, v167, 16, 1
	v_lshrrev_b32_e32 v143, 16, v143
	v_add3_u32 v145, v167, v145, s62
	ds_read2_b32 v[170:171], v138 offset0:198 offset1:231
	v_and_or_b32 v165, v145, s63, v143
	s_waitcnt lgkmcnt(1)
	v_bfe_u32 v143, v168, 16, 1
	v_add3_u32 v143, v168, v143, s62
	v_lshrrev_b32_e32 v138, 16, v143
	v_bfe_u32 v143, v169, 16, 1
	v_add_u32_e32 v144, 24, v144
	v_add3_u32 v143, v169, v143, s62
	v_ashrrev_i32_e32 v145, 31, v144
	v_and_or_b32 v166, v143, s63, v138
	s_waitcnt lgkmcnt(0)
	v_bfe_u32 v138, v170, 16, 1
	v_lshlrev_b64 v[144:145], 11, v[144:145]
	v_add3_u32 v138, v170, v138, s62
	v_bfe_u32 v143, v171, 16, 1
	v_lshl_add_u64 v[144:145], s[78:79], 0, v[144:145]
	v_lshrrev_b32_e32 v138, 16, v138
	v_add3_u32 v143, v171, v143, s62
	v_lshl_add_u64 v[144:145], v[144:145], 0, s[92:93]
	v_and_or_b32 v167, v143, s63, v138
	v_lshl_add_u64 v[144:145], v[144:145], 0, v[134:135]
	global_store_dwordx4 v[144:145], v[164:167], off nt
	s_waitcnt lgkmcnt(0)
	s_cmpk_gt_i32 s95, 0xa0f
	s_cbranch_scc1 .LBB0_98
; __device__ __forceinline__ void win_block(int nb, int& src0, bool& perm) {
;     const int n = nb * 32; perm = false;
;     if (n < 2560) { src0 = n; }
;     else if (n < 3584) { const int j = n - 2560; src0 = 2592 + j; perm = ((j & 63) == 0); }
;     else if (n < 3840) { const int j = n - 3584; src0 = 3616 + j; perm = ((j & 63) == 0); }
;     else if (n < 4096) { src0 = 3872 + (n - 3840); }
;     else if (n < 5120) { src0 = 4128 + (n - 4096); }
;     else { src0 = 2560 + (n - 5120); }
; }
	s_mul_hi_i32 s10, s95, 0xcb8727c1
	s_add_i32 s10, s10, s95
	s_lshr_b32 s11, s10, 31
	s_ashr_i32 s10, s10, 7
	s_add_i32 s11, s10, s11
	s_mul_i32 s10, s11, 0xa1
	s_sub_i32 s83, s95, s10
	s_lshl_b32 s94, s83, 5
	s_mov_b64 s[84:85], 0
	s_cmpk_lt_i32 s83, 0x50
	s_mov_b32 s10, s94
	s_cbranch_scc1 .LBB0_96
	s_cmpk_gt_u32 s83, 0x6f
	s_mov_b64 s[14:15], -1
	s_cbranch_scc0 .LBB0_94
	s_cmpk_gt_u32 s83, 0x77
	s_mov_b64 s[84:85], -1
	s_cbranch_scc0 .LBB0_92
	s_cmpk_gt_u32 s83, 0x7f
	s_cbranch_scc0 .LBB0_89
	s_add_i32 s10, s94, 32
	s_cmpk_lt_u32 s83, 0xa0
	s_cselect_b32 s10, s10, 0xa00
	s_mov_b64 s[14:15], 0

; #define GAS __attribute__((address_space(1)))
; #define LAS __attribute__((address_space(3)))
; #define LDS_WAIT() asm volatile("s_waitcnt lgkmcnt(0)" ::: "memory")
; __device__ __forceinline__ unsigned pk2(float lo, float hi) { return f2bf(lo) | (f2bf(hi) << 16); }
; __device__ __forceinline__ void p0_item_store(const P0Item& I, const float (&wv)[32], LAS float* scr, int lane) {
; #pragma unroll
;     for (int i = 0; i < 8; ++i) { const int kk = 8 * i + (lane >> 3); const float s = I.scale ? I.scale[I.k0 + kk] : 1.f; LAS float* d = scr + kk * 33 + 4 * (lane & 7);
;         d[0] = wv[4 * i] * s; d[1] = wv[4 * i + 1] * s; d[2] = wv[4 * i + 2] * s; d[3] = wv[4 * i + 3] * s; }
;     LDS_WAIT(); asm volatile("" ::: "memory");
;     const int c = lane & 7;
; #pragma unroll
;     for (int j = 0; j < 4; ++j) { const int n = (lane >> 3) + 8 * j; const int ns = I.perm ? rope_perm(n) : n; const LAS float* s = scr + (8 * c) * 33 + ns;
;         v4u o; o.x = pk2(s[0 * 33], s[1 * 33]); o.y = pk2(s[2 * 33], s[3 * 33]); o.z = pk2(s[4 * 33], s[5 * 33]); o.w = pk2(s[6 * 33], s[7 * 33]);
;         *(GAS v4u*)(I.WT + (size_t)(I.out_row0 + n) * I.K + I.k0 + 8 * c) = o; }
;     LDS_WAIT(); asm volatile("" ::: "memory");
; }
; __device__ __forceinline__ void p0_prologue(Frame& F, const Ptrs& P) {
;     ...
;         for (int it = gw; it < NITEMS; it += 3 * NGW) {
;             const bool h1 = it + NGW < NITEMS, h2 = it + 2 * NGW < NITEMS;
;             P0_DECODE(Ia, it); p0_item_load(Ia, wa, lane);
;             if (h1) { P0_DECODE(Ib, it + NGW); p0_item_load(Ib, wb, lane); }
;             p0_item_store(Ia, wa, scr, lane);
;             if (h2) { P0_DECODE(Ia, it + 2 * NGW); p0_item_load(Ia, wa, lane); }
;             if (h1) p0_item_store(Ib, wb, scr, lane);
;             if (h2) p0_item_store(Ia, wa, scr, lane);
;         }
.LBB0_111:
	s_waitcnt vmcnt(0)
	v_pk_mul_f32 v[144:145], v[88:89], v[138:139] op_sel_hi:[1,0]
	ds_write2_b32 v139, v144, v145 offset1:1
	v_pk_mul_f32 v[144:145], v[90:91], v[138:139] op_sel_hi:[1,0]
	ds_write2_b32 v140, v144, v145 offset1:1
	s_and_b64 vcc, s[0:1], s[80:81]
	s_waitcnt lgkmcnt(0)
	v_cndmask_b32_e32 v138, v132, v154, vcc
	v_lshl_add_u32 v138, v138, 2, v153
	ds_read2_b32 v[144:145], v138 offset1:33
	s_lshl_b64 s[10:11], s[82:83], 1
	s_and_b64 vcc, s[2:3], s[80:81]
	s_waitcnt lgkmcnt(0)
	v_bfe_u32 v143, v144, 16, 1
	v_add3_u32 v143, v144, v143, s62
	v_bfe_u32 v144, v145, 16, 1
	v_lshrrev_b32_e32 v143, 16, v143
	v_add3_u32 v144, v145, v144, s62
	v_and_or_b32 v164, v144, s63, v143
	ds_read2_b32 v[144:145], v138 offset0:66 offset1:99
	s_waitcnt lgkmcnt(0)
	v_bfe_u32 v143, v144, 16, 1
	v_add3_u32 v143, v144, v143, s62
	v_bfe_u32 v144, v145, 16, 1
	v_lshrrev_b32_e32 v143, 16, v143
	v_add3_u32 v144, v145, v144, s62
	v_and_or_b32 v165, v144, s63, v143
	ds_read2_b32 v[144:145], v138 offset0:132 offset1:165
	s_waitcnt lgkmcnt(0)
	v_bfe_u32 v143, v144, 16, 1
	v_add3_u32 v143, v144, v143, s62
	v_bfe_u32 v144, v145, 16, 1
	v_lshrrev_b32_e32 v143, 16, v143
	v_add3_u32 v144, v145, v144, s62
	v_and_or_b32 v166, v144, s63, v143
	ds_read2_b32 v[144:145], v138 offset0:198 offset1:231
	s_waitcnt lgkmcnt(0)
	v_bfe_u32 v138, v144, 16, 1
	v_add3_u32 v138, v144, v138, s62
	v_bfe_u32 v143, v145, 16, 1
	v_add_u32_e32 v144, s65, v132
	v_add3_u32 v143, v145, v143, s62
	v_ashrrev_i32_e32 v145, 31, v144
	v_lshlrev_b64 v[144:145], 11, v[144:145]
	v_lshrrev_b32_e32 v138, 16, v138
	v_lshl_add_u64 v[144:145], s[78:79], 0, v[144:145]
	v_and_or_b32 v167, v143, s63, v138
	v_lshl_add_u64 v[144:145], v[144:145], 0, s[10:11]
	v_cndmask_b32_e32 v138, v149, v155, vcc
	v_lshl_add_u64 v[144:145], v[144:145], 0, v[134:135]
	v_lshl_add_u32 v138, v138, 2, v153
	global_store_dwordx4 v[144:145], v[164:167], off nt
	ds_read2_b32 v[144:145], v138 offset1:33
	s_and_b64 vcc, s[4:5], s[80:81]
	s_waitcnt lgkmcnt(0)
	v_bfe_u32 v143, v144, 16, 1
	v_add3_u32 v143, v144, v143, s62
	v_bfe_u32 v144, v145, 16, 1
	v_lshrrev_b32_e32 v143, 16, v143
	v_add3_u32 v144, v145, v144, s62
	v_and_or_b32 v164, v144, s63, v143
	ds_read2_b32 v[144:145], v138 offset0:66 offset1:99
	s_waitcnt lgkmcnt(0)
	v_bfe_u32 v143, v144, 16, 1
	v_add3_u32 v143, v144, v143, s62
	v_bfe_u32 v144, v145, 16, 1
	v_lshrrev_b32_e32 v143, 16, v143
	v_add3_u32 v144, v145, v144, s62
	v_and_or_b32 v165, v144, s63, v143
	ds_read2_b32 v[144:145], v138 offset0:132 offset1:165
	s_waitcnt lgkmcnt(0)
	v_bfe_u32 v143, v144, 16, 1
	v_add3_u32 v143, v144, v143, s62
	v_bfe_u32 v144, v145, 16, 1
	v_lshrrev_b32_e32 v143, 16, v143
	v_add3_u32 v144, v145, v144, s62
	v_and_or_b32 v166, v144, s63, v143
	ds_read2_b32 v[144:145], v138 offset0:198 offset1:231
	s_waitcnt lgkmcnt(0)
	v_bfe_u32 v138, v144, 16, 1
	v_add3_u32 v138, v144, v138, s62
	v_bfe_u32 v143, v145, 16, 1
	v_add_u32_e32 v144, s65, v149
	v_add3_u32 v143, v145, v143, s62
	v_ashrrev_i32_e32 v145, 31, v144
	v_lshlrev_b64 v[144:145], 11, v[144:145]
	v_lshrrev_b32_e32 v138, 16, v138
	v_lshl_add_u64 v[144:145], s[78:79], 0, v[144:145]
	v_and_or_b32 v167, v143, s63, v138
	v_lshl_add_u64 v[144:145], v[144:145], 0, s[10:11]
	v_cndmask_b32_e32 v138, v151, v156, vcc
	v_lshl_add_u64 v[144:145], v[144:145], 0, v[134:135]
	v_lshl_add_u32 v138, v138, 2, v153
	global_store_dwordx4 v[144:145], v[164:167], off nt
	ds_read2_b32 v[144:145], v138 offset1:33
	s_and_b64 vcc, s[6:7], s[80:81]
	s_waitcnt lgkmcnt(0)
	v_bfe_u32 v143, v144, 16, 1
	v_add3_u32 v143, v144, v143, s62
	v_bfe_u32 v144, v145, 16, 1
	v_lshrrev_b32_e32 v143, 16, v143
	v_add3_u32 v144, v145, v144, s62
	v_and_or_b32 v164, v144, s63, v143
	ds_read2_b32 v[144:145], v138 offset0:66 offset1:99
	s_waitcnt lgkmcnt(0)
	v_bfe_u32 v143, v144, 16, 1
	v_add3_u32 v143, v144, v143, s62
	v_bfe_u32 v144, v145, 16, 1
	v_lshrrev_b32_e32 v143, 16, v143
	v_add3_u32 v144, v145, v144, s62
	v_and_or_b32 v165, v144, s63, v143
	ds_read2_b32 v[144:145], v138 offset0:132 offset1:165
	s_waitcnt lgkmcnt(0)
	v_bfe_u32 v143, v144, 16, 1
	v_add3_u32 v143, v144, v143, s62
	v_bfe_u32 v144, v145, 16, 1
	v_lshrrev_b32_e32 v143, 16, v143
	v_add3_u32 v144, v145, v144, s62
	v_and_or_b32 v166, v144, s63, v143
	ds_read2_b32 v[144:145], v138 offset0:198 offset1:231
	s_waitcnt lgkmcnt(0)
	v_bfe_u32 v138, v144, 16, 1
	v_add3_u32 v138, v144, v138, s62
	v_bfe_u32 v143, v145, 16, 1
	v_add_u32_e32 v144, s65, v151
	v_add3_u32 v143, v145, v143, s62
	v_ashrrev_i32_e32 v145, 31, v144
	v_lshlrev_b64 v[144:145], 11, v[144:145]
	v_lshrrev_b32_e32 v138, 16, v138
	v_lshl_add_u64 v[144:145], s[78:79], 0, v[144:145]
	v_and_or_b32 v167, v143, s63, v138
	v_lshl_add_u64 v[144:145], v[144:145], 0, s[10:11]
	v_cndmask_b32_e32 v138, v152, v157, vcc
	v_lshl_add_u64 v[144:145], v[144:145], 0, v[134:135]
	v_lshl_add_u32 v138, v138, 2, v153
	global_store_dwordx4 v[144:145], v[164:167], off nt
	ds_read2_b32 v[144:145], v138 offset1:33
	s_waitcnt lgkmcnt(0)
	v_bfe_u32 v143, v144, 16, 1
	v_add3_u32 v143, v144, v143, s62
	v_bfe_u32 v144, v145, 16, 1
	v_lshrrev_b32_e32 v143, 16, v143
	v_add3_u32 v144, v145, v144, s62
	v_and_or_b32 v164, v144, s63, v143
	ds_read2_b32 v[144:145], v138 offset0:66 offset1:99
	s_waitcnt lgkmcnt(0)
	v_bfe_u32 v143, v144, 16, 1
	v_add3_u32 v143, v144, v143, s62
	v_bfe_u32 v144, v145, 16, 1
	v_lshrrev_b32_e32 v143, 16, v143
	v_add3_u32 v144, v145, v144, s62
	v_and_or_b32 v165, v144, s63, v143
	ds_read2_b32 v[144:145], v138 offset0:132 offset1:165
	s_waitcnt lgkmcnt(0)
	v_bfe_u32 v143, v144, 16, 1
	v_add3_u32 v143, v144, v143, s62
	v_bfe_u32 v144, v145, 16, 1
	v_lshrrev_b32_e32 v143, 16, v143
	v_add3_u32 v144, v145, v144, s62
	v_and_or_b32 v166, v144, s63, v143
	ds_read2_b32 v[144:145], v138 offset0:198 offset1:231
	s_waitcnt lgkmcnt(0)
	v_bfe_u32 v138, v144, 16, 1
	v_add3_u32 v138, v144, v138, s62
	v_bfe_u32 v143, v145, 16, 1
	v_add_u32_e32 v144, s65, v152
	v_add3_u32 v143, v145, v143, s62
	v_ashrrev_i32_e32 v145, 31, v144
	v_lshlrev_b64 v[144:145], 11, v[144:145]
	v_lshl_add_u64 v[144:145], s[78:79], 0, v[144:145]
	v_lshrrev_b32_e32 v138, 16, v138
	v_lshl_add_u64 v[144:145], v[144:145], 0, s[10:11]
	v_and_or_b32 v167, v143, s63, v138
	v_lshl_add_u64 v[144:145], v[144:145], 0, v[134:135]
	global_store_dwordx4 v[144:145], v[164:167], off nt
	s_waitcnt lgkmcnt(0)
	s_andn2_b64 vcc, exec, s[88:89]
	s_cbranch_vccnz .LBB0_48

; #define GAS __attribute__((address_space(1)))
; __device__ __forceinline__ float wave_sum(float v) {
; #pragma unroll
;     for (int o = 1; o < 64; o <<= 1) v += __shfl_xor(v, o);
;     return v;
; }
; __device__ __forceinline__ void p0_prologue(Frame& F, const Ptrs& P) {
;     ...
;     {
;         f32x4 vb[4][4];
; #pragma unroll
;         for (int r = 0; r < 4; ++r) { const GAS f32x4* xr = (const GAS f32x4*)(P.x + (size_t)(gw + (4 + r) * NGW) * DM) + lane;
; #pragma unroll
;             for (int j = 0; j < 4; ++j) vb[r][j] = xr[64 * j]; }
;         P0_XROWS(va, gw);
;         P0_XROWS(vb, gw + 4 * NGW);
.LBB0_131:
	s_add_u32 s14, s96, 0x180000
	s_addc_u32 s15, s97, 0
	s_add_u32 s20, s96, 0x1400000
	v_readlane_b32 s0, v252, 2
	s_addc_u32 s21, s97, 0
	s_lshl_b32 s0, s0, 5
	s_add_i32 s6, s70, s0
	s_ashr_i32 s7, s6, 31
	s_lshl_b64 s[0:1], s[6:7], 12
	s_add_u32 s0, s16, s0
	s_addc_u32 s1, s17, s1
	s_add_i32 s8, s6, s33
	s_ashr_i32 s9, s8, 31
	v_lshl_add_u64 v[64:65], s[0:1], 0, v[130:131]
	s_lshl_b64 s[0:1], s[8:9], 12
	s_add_u32 s0, s16, s0
	s_addc_u32 s1, s17, s1
	global_load_dwordx4 v[124:127], v[64:65], off nt
	global_load_dwordx4 v[120:123], v[64:65], off offset:1024 nt
	global_load_dwordx4 v[116:119], v[64:65], off offset:2048 nt
	global_load_dwordx4 v[112:115], v[64:65], off offset:3072 nt
	v_lshl_add_u64 v[64:65], s[0:1], 0, v[130:131]
	s_add_i32 s0, s8, s33
	s_ashr_i32 s1, s0, 31
	s_lshl_b64 s[2:3], s[0:1], 12
	s_add_u32 s2, s16, s2
	s_addc_u32 s3, s17, s3
	s_add_i32 s0, s0, s33
	s_ashr_i32 s1, s0, 31
	s_lshl_b64 s[0:1], s[0:1], 12
	s_add_u32 s0, s16, s0
	global_load_dwordx4 v[108:111], v[64:65], off nt
	global_load_dwordx4 v[104:107], v[64:65], off offset:1024 nt
	global_load_dwordx4 v[100:103], v[64:65], off offset:2048 nt
	global_load_dwordx4 v[96:99], v[64:65], off offset:3072 nt
	v_lshl_add_u64 v[64:65], s[2:3], 0, v[130:131]
	s_addc_u32 s1, s17, s1
	global_load_dwordx4 v[92:95], v[64:65], off nt
	global_load_dwordx4 v[88:91], v[64:65], off offset:1024 nt
	global_load_dwordx4 v[84:87], v[64:65], off offset:2048 nt
	global_load_dwordx4 v[80:83], v[64:65], off offset:3072 nt
	v_lshl_add_u64 v[64:65], s[0:1], 0, v[130:131]
	global_load_dwordx4 v[76:79], v[64:65], off nt
	global_load_dwordx4 v[72:75], v[64:65], off offset:1024 nt
	global_load_dwordx4 v[68:71], v[64:65], off offset:2048 nt
	s_nop 0
	global_load_dwordx4 v[64:67], v[64:65], off offset:3072 nt
	s_waitcnt vmcnt(31)
	v_mul_f32_e32 v132, v61, v61
	v_mul_f32_e32 v133, v63, v63
	v_fmac_f32_e32 v132, v60, v60
	v_fmac_f32_e32 v133, v62, v62
	v_add_f32_e32 v132, v132, v133
	s_waitcnt vmcnt(30)
	v_mul_f32_e32 v133, v57, v57
	v_mul_f32_e32 v135, v59, v59
	v_fmac_f32_e32 v133, v56, v56
	v_fmac_f32_e32 v135, v58, v58
	v_add_f32_e32 v133, v133, v135
	v_mbcnt_lo_u32_b32 v130, -1, 0
	v_add_f32_e32 v132, v132, v133
	s_waitcnt vmcnt(29)
	v_mul_f32_e32 v133, v53, v53
	v_mul_f32_e32 v135, v55, v55
	v_mbcnt_hi_u32_b32 v134, -1, v130
	v_fmac_f32_e32 v133, v52, v52
	v_fmac_f32_e32 v135, v54, v54
	v_and_b32_e32 v130, 64, v134
	v_add_f32_e32 v133, v133, v135
	v_add_u32_e32 v136, 64, v130
	v_xor_b32_e32 v130, 1, v134
	v_add_f32_e32 v132, v132, v133
	s_waitcnt vmcnt(28)
	v_mul_f32_e32 v133, v49, v49
	v_mul_f32_e32 v135, v51, v51
	v_cmp_lt_i32_e32 vcc, v130, v136
	v_fmac_f32_e32 v133, v48, v48
	v_fmac_f32_e32 v135, v50, v50
	v_cndmask_b32_e32 v130, v134, v130, vcc
	v_add_f32_e32 v133, v133, v135
	v_lshlrev_b32_e32 v130, 2, v130
	v_add_f32_e32 v132, v132, v133
	ds_bpermute_b32 v133, v130, v132
	v_xor_b32_e32 v131, 2, v134
	v_cmp_lt_i32_e32 vcc, v131, v136
	v_xor_b32_e32 v135, 4, v134
	v_bfe_u32 v140, v60, 16, 1
	v_cndmask_b32_e32 v131, v134, v131, vcc
	v_lshlrev_b32_e32 v131, 2, v131
	s_waitcnt lgkmcnt(0)
	v_add_f32_e32 v133, v132, v133
	ds_bpermute_b32 v137, v131, v133
	v_cmp_lt_i32_e32 vcc, v135, v136
	s_movk_i32 s16, 0x7fff
	v_add3_u32 v60, v60, v140, s16
	v_cndmask_b32_e32 v132, v134, v135, vcc
	v_lshlrev_b32_e32 v132, 2, v132
	s_waitcnt lgkmcnt(0)
	v_add_f32_e32 v137, v133, v137
	ds_bpermute_b32 v138, v132, v137
	v_xor_b32_e32 v135, 8, v134
	v_cmp_lt_i32_e32 vcc, v135, v136
	v_bfe_u32 v140, v61, 16, 1
	v_lshrrev_b32_e32 v60, 16, v60
	v_cndmask_b32_e32 v133, v134, v135, vcc
	v_lshlrev_b32_e32 v133, 2, v133
	s_waitcnt lgkmcnt(0)
	v_add_f32_e32 v137, v137, v138
	ds_bpermute_b32 v138, v133, v137
	v_xor_b32_e32 v135, 16, v134
	v_cmp_lt_i32_e32 vcc, v135, v136
	v_add3_u32 v61, v61, v140, s16
	s_mov_b32 s17, 0xffff0000
	v_cndmask_b32_e32 v135, v134, v135, vcc
	v_lshlrev_b32_e32 v135, 2, v135
	s_waitcnt lgkmcnt(0)
	v_add_f32_e32 v137, v137, v138
	ds_bpermute_b32 v138, v135, v137
	s_lshl_b64 s[4:5], s[70:71], 11
	v_and_or_b32 v60, v61, s17, v60
	v_bfe_u32 v61, v62, 16, 1
	v_xor_b32_e32 v139, 32, v134
	s_add_u32 s2, s20, s4
	v_add3_u32 v61, v62, v61, s16
	v_bfe_u32 v62, v63, 16, 1
	v_cmp_lt_i32_e32 vcc, v139, v136
	s_addc_u32 s3, s21, s5
	v_lshrrev_b32_e32 v61, 16, v61
	v_add3_u32 v62, v63, v62, s16
	v_cndmask_b32_e32 v134, v134, v139, vcc
	s_waitcnt lgkmcnt(0)
	v_add_f32_e32 v136, v137, v138
	v_lshl_add_u64 v[138:139], v[128:129], 3, s[2:3]
	v_and_or_b32 v61, v62, s17, v61
	global_store_dwordx2 v[138:139], v[60:61], off nt
	v_bfe_u32 v60, v56, 16, 1
	v_add3_u32 v56, v56, v60, s16
	v_bfe_u32 v60, v57, 16, 1
	v_lshrrev_b32_e32 v56, 16, v56
	v_add3_u32 v57, v57, v60, s16
	v_and_or_b32 v56, v57, s17, v56
	v_bfe_u32 v57, v58, 16, 1
	v_add3_u32 v57, v58, v57, s16
	v_bfe_u32 v58, v59, 16, 1
	v_lshrrev_b32_e32 v57, 16, v57
	v_add3_u32 v58, v59, v58, s16
	v_and_or_b32 v57, v58, s17, v57
	global_store_dwordx2 v[138:139], v[56:57], off offset:512 nt
	v_bfe_u32 v56, v52, 16, 1
	v_add3_u32 v52, v52, v56, s16
	v_bfe_u32 v56, v53, 16, 1
	v_lshrrev_b32_e32 v52, 16, v52
	v_add3_u32 v53, v53, v56, s16
	v_and_or_b32 v52, v53, s17, v52
	v_bfe_u32 v53, v54, 16, 1
	v_add3_u32 v53, v54, v53, s16
	v_bfe_u32 v54, v55, 16, 1
	v_lshrrev_b32_e32 v53, 16, v53
	v_add3_u32 v54, v55, v54, s16
	v_and_or_b32 v53, v54, s17, v53
	global_store_dwordx2 v[138:139], v[52:53], off offset:1024 nt
	v_bfe_u32 v52, v48, 16, 1
	v_lshlrev_b32_e32 v134, 2, v134
	v_add3_u32 v48, v48, v52, s16
	v_bfe_u32 v52, v49, 16, 1
	ds_bpermute_b32 v137, v134, v136
	v_lshrrev_b32_e32 v48, 16, v48
	v_add3_u32 v49, v49, v52, s16
	v_and_or_b32 v48, v49, s17, v48
	v_bfe_u32 v49, v50, 16, 1
	v_add3_u32 v49, v50, v49, s16
	v_bfe_u32 v50, v51, 16, 1
	v_lshrrev_b32_e32 v49, 16, v49
	v_add3_u32 v50, v51, v50, s16
	v_cmp_eq_u32_e64 s[0:1], 0, v128
	v_and_or_b32 v49, v50, s17, v49
	global_store_dwordx2 v[138:139], v[48:49], off offset:1536 nt
	s_and_saveexec_b64 s[10:11], s[0:1]
	s_cbranch_execz .LBB0_133
	s_waitcnt lgkmcnt(0)
	v_add_f32_e32 v48, v136, v137
	v_mov_b32_e32 v49, 0x358637bd
	v_fmac_f32_e32 v49, 0x3a800000, v48
	s_mov_b32 s2, 0xf800000
	v_mul_f32_e32 v48, 0x4f800000, v49
	v_cmp_gt_f32_e32 vcc, s2, v49
	s_nop 1
	v_cndmask_b32_e32 v48, v49, v48, vcc
	v_sqrt_f32_e32 v49, v48
	s_nop 0
	v_add_u32_e32 v50, -1, v49
	v_fma_f32 v51, -v50, v49, v48
	v_cmp_ge_f32_e64 s[2:3], 0, v51
	v_add_u32_e32 v51, 1, v49
	s_nop 0
	v_cndmask_b32_e64 v50, v49, v50, s[2:3]
	v_fma_f32 v49, -v51, v49, v48
	v_cmp_lt_f32_e64 s[2:3], 0, v49
	s_nop 1
	v_cndmask_b32_e64 v49, v50, v51, s[2:3]
	v_mul_f32_e32 v50, 0x37800000, v49
	v_cndmask_b32_e32 v49, v49, v50, vcc
	v_mov_b32_e32 v50, 0x260
	v_cmp_class_f32_e32 vcc, v48, v50
	s_nop 1
	v_cndmask_b32_e32 v48, v49, v48, vcc
	v_div_scale_f32 v49, s[2:3], v48, v48, 1.0
	v_rcp_f32_e32 v50, v49
	s_lshl_b64 s[2:3], s[70:71], 2
	s_add_u32 s2, s14, s2
	s_addc_u32 s3, s15, s3
	v_fma_f32 v51, -v49, v50, 1.0
	v_fmac_f32_e32 v50, v51, v50
	v_div_scale_f32 v51, vcc, 1.0, v48, 1.0
	v_mul_f32_e32 v52, v51, v50
	v_fma_f32 v53, -v49, v52, v51
	v_fmac_f32_e32 v52, v53, v50
	v_fma_f32 v49, -v49, v52, v51
	v_div_fmas_f32 v49, v49, v50, v52
	v_div_fixup_f32 v48, v49, v48, 1.0
	v_mov_b32_e32 v49, 0
	global_store_dword v49, v48, s[2:3]
.LBB0_133:
	s_or_b64 exec, exec, s[10:11]
	s_waitcnt vmcnt(31)
	v_mul_f32_e32 v48, v45, v45
	v_mul_f32_e32 v49, v47, v47
	v_fmac_f32_e32 v48, v44, v44
	v_fmac_f32_e32 v49, v46, v46
	v_add_f32_e32 v48, v48, v49
	s_waitcnt vmcnt(30)
	v_mul_f32_e32 v49, v41, v41
	v_mul_f32_e32 v50, v43, v43
	v_fmac_f32_e32 v49, v40, v40
	v_fmac_f32_e32 v50, v42, v42
	v_add_f32_e32 v49, v49, v50
	v_add_f32_e32 v48, v48, v49
	s_waitcnt vmcnt(29)
	v_mul_f32_e32 v49, v37, v37
	v_mul_f32_e32 v50, v39, v39
	v_fmac_f32_e32 v49, v36, v36
	v_fmac_f32_e32 v50, v38, v38
	v_add_f32_e32 v49, v49, v50
	v_add_f32_e32 v48, v48, v49
	s_waitcnt vmcnt(28)
	v_mul_f32_e32 v49, v33, v33
	v_mul_f32_e32 v50, v35, v35
	v_fmac_f32_e32 v49, v32, v32
	v_fmac_f32_e32 v50, v34, v34
	v_add_f32_e32 v49, v49, v50
	v_add_f32_e32 v48, v48, v49
	ds_bpermute_b32 v49, v130, v48
	v_bfe_u32 v52, v44, 16, 1
	v_add3_u32 v44, v44, v52, s16
	v_bfe_u32 v52, v45, 16, 1
	v_lshrrev_b32_e32 v44, 16, v44
	s_waitcnt lgkmcnt(0)
	v_add_f32_e32 v48, v48, v49
	ds_bpermute_b32 v49, v131, v48
	v_add3_u32 v45, v45, v52, s16
	s_lshl_b64 s[2:3], s[76:77], 11
	v_and_or_b32 v44, v45, s17, v44
	v_bfe_u32 v45, v46, 16, 1
	s_waitcnt lgkmcnt(0)
	v_add_f32_e32 v48, v48, v49
	s_add_u32 s2, s20, s2
	v_add3_u32 v45, v46, v45, s16
	v_bfe_u32 v46, v47, 16, 1
	ds_bpermute_b32 v49, v132, v48
	s_addc_u32 s3, s21, s3
	v_lshrrev_b32_e32 v45, 16, v45
	v_add3_u32 v46, v47, v46, s16
	v_lshl_add_u64 v[50:51], v[128:129], 3, s[2:3]
	v_and_or_b32 v45, v46, s17, v45
	global_store_dwordx2 v[50:51], v[44:45], off nt
	v_bfe_u32 v44, v40, 16, 1
	v_add3_u32 v40, v40, v44, s16
	v_bfe_u32 v44, v41, 16, 1
	v_lshrrev_b32_e32 v40, 16, v40
	v_add3_u32 v41, v41, v44, s16
	s_waitcnt lgkmcnt(0)
	v_add_f32_e32 v48, v48, v49
	v_and_or_b32 v40, v41, s17, v40
	v_bfe_u32 v41, v42, 16, 1
	ds_bpermute_b32 v49, v133, v48
	v_add3_u32 v41, v42, v41, s16
	v_bfe_u32 v42, v43, 16, 1
	v_lshrrev_b32_e32 v41, 16, v41
	v_add3_u32 v42, v43, v42, s16
	v_and_or_b32 v41, v42, s17, v41
	global_store_dwordx2 v[50:51], v[40:41], off offset:512 nt
	v_bfe_u32 v40, v36, 16, 1
	v_add3_u32 v36, v36, v40, s16
	v_bfe_u32 v40, v37, 16, 1
	s_waitcnt lgkmcnt(0)
	v_add_f32_e32 v48, v48, v49
	v_lshrrev_b32_e32 v36, 16, v36
	v_add3_u32 v37, v37, v40, s16
	ds_bpermute_b32 v49, v135, v48
	v_and_or_b32 v36, v37, s17, v36
	v_bfe_u32 v37, v38, 16, 1
	v_add3_u32 v37, v38, v37, s16
	v_bfe_u32 v38, v39, 16, 1
	v_lshrrev_b32_e32 v37, 16, v37
	v_add3_u32 v38, v39, v38, s16
	v_and_or_b32 v37, v38, s17, v37
	global_store_dwordx2 v[50:51], v[36:37], off offset:1024 nt
	v_bfe_u32 v36, v32, 16, 1
	s_waitcnt lgkmcnt(0)
	v_add_f32_e32 v48, v48, v49
	v_add3_u32 v32, v32, v36, s16
	v_bfe_u32 v36, v33, 16, 1
	ds_bpermute_b32 v49, v134, v48
	v_lshrrev_b32_e32 v32, 16, v32
	v_add3_u32 v33, v33, v36, s16
	v_and_or_b32 v32, v33, s17, v32
	v_bfe_u32 v33, v34, 16, 1
	v_add3_u32 v33, v34, v33, s16
	v_bfe_u32 v34, v35, 16, 1
	v_lshrrev_b32_e32 v33, 16, v33
	v_add3_u32 v34, v35, v34, s16
	v_and_or_b32 v33, v34, s17, v33
	global_store_dwordx2 v[50:51], v[32:33], off offset:1536 nt
	s_and_saveexec_b64 s[10:11], s[0:1]
	s_cbranch_execz .LBB0_135
	s_waitcnt lgkmcnt(0)
	v_add_f32_e32 v32, v48, v49
	v_mov_b32_e32 v33, 0x358637bd
	v_fmac_f32_e32 v33, 0x3a800000, v32
	s_mov_b32 s2, 0xf800000
	v_mul_f32_e32 v32, 0x4f800000, v33
	v_cmp_gt_f32_e32 vcc, s2, v33
	s_nop 1
	v_cndmask_b32_e32 v32, v33, v32, vcc
	v_sqrt_f32_e32 v33, v32
	s_nop 0
	v_add_u32_e32 v34, -1, v33
	v_fma_f32 v35, -v34, v33, v32
	v_cmp_ge_f32_e64 s[2:3], 0, v35
	v_add_u32_e32 v35, 1, v33
	s_nop 0
	v_cndmask_b32_e64 v34, v33, v34, s[2:3]
	v_fma_f32 v33, -v35, v33, v32
	v_cmp_lt_f32_e64 s[2:3], 0, v33
	s_nop 1
	v_cndmask_b32_e64 v33, v34, v35, s[2:3]
	v_mul_f32_e32 v34, 0x37800000, v33
	v_cndmask_b32_e32 v33, v33, v34, vcc
	v_mov_b32_e32 v34, 0x260
	v_cmp_class_f32_e32 vcc, v32, v34
	s_nop 1
	v_cndmask_b32_e32 v32, v33, v32, vcc
	v_div_scale_f32 v33, s[2:3], v32, v32, 1.0
	v_rcp_f32_e32 v34, v33
	s_lshl_b64 s[2:3], s[76:77], 2
	s_add_u32 s2, s14, s2
	s_addc_u32 s3, s15, s3
	v_fma_f32 v35, -v33, v34, 1.0
	v_fmac_f32_e32 v34, v35, v34
	v_div_scale_f32 v35, vcc, 1.0, v32, 1.0
	v_mul_f32_e32 v36, v35, v34
	v_fma_f32 v37, -v33, v36, v35
	v_fmac_f32_e32 v36, v37, v34
	v_fma_f32 v33, -v33, v36, v35
	v_div_fmas_f32 v33, v33, v34, v36
	v_div_fixup_f32 v32, v33, v32, 1.0
	v_mov_b32_e32 v33, 0
	global_store_dword v33, v32, s[2:3]
.LBB0_135:
	s_or_b64 exec, exec, s[10:11]
	s_waitcnt vmcnt(31)
	v_mul_f32_e32 v32, v29, v29
	v_mul_f32_e32 v33, v31, v31
	v_fmac_f32_e32 v32, v28, v28
	v_fmac_f32_e32 v33, v30, v30
	v_add_f32_e32 v32, v32, v33
	s_waitcnt vmcnt(30)
	v_mul_f32_e32 v33, v25, v25
	v_mul_f32_e32 v34, v27, v27
	v_fmac_f32_e32 v33, v24, v24
	v_fmac_f32_e32 v34, v26, v26
	v_add_f32_e32 v33, v33, v34
	v_add_f32_e32 v32, v32, v33
	s_waitcnt vmcnt(29)
	v_mul_f32_e32 v33, v21, v21
	v_mul_f32_e32 v34, v23, v23
	v_fmac_f32_e32 v33, v20, v20
	v_fmac_f32_e32 v34, v22, v22
	v_add_f32_e32 v33, v33, v34
	v_add_f32_e32 v32, v32, v33
	s_waitcnt vmcnt(28)
	v_mul_f32_e32 v33, v17, v17
	v_mul_f32_e32 v34, v19, v19
	v_fmac_f32_e32 v33, v16, v16
	v_fmac_f32_e32 v34, v18, v18
	v_add_f32_e32 v33, v33, v34
	v_add_f32_e32 v32, v32, v33
	ds_bpermute_b32 v33, v130, v32
	v_bfe_u32 v36, v28, 16, 1
	v_add3_u32 v28, v28, v36, s16
	v_bfe_u32 v36, v29, 16, 1
	v_lshrrev_b32_e32 v28, 16, v28
	s_waitcnt lgkmcnt(0)
	v_add_f32_e32 v32, v32, v33
	ds_bpermute_b32 v33, v131, v32
	v_add3_u32 v29, v29, v36, s16
	s_lshl_b64 s[2:3], s[74:75], 11
	v_and_or_b32 v28, v29, s17, v28
	v_bfe_u32 v29, v30, 16, 1
	s_waitcnt lgkmcnt(0)
	v_add_f32_e32 v32, v32, v33
	s_add_u32 s2, s20, s2
	v_add3_u32 v29, v30, v29, s16
	v_bfe_u32 v30, v31, 16, 1
	ds_bpermute_b32 v33, v132, v32
	s_addc_u32 s3, s21, s3
	v_lshrrev_b32_e32 v29, 16, v29
	v_add3_u32 v30, v31, v30, s16
	v_lshl_add_u64 v[34:35], v[128:129], 3, s[2:3]
	v_and_or_b32 v29, v30, s17, v29
	global_store_dwordx2 v[34:35], v[28:29], off nt
	v_bfe_u32 v28, v24, 16, 1
	v_add3_u32 v24, v24, v28, s16
	v_bfe_u32 v28, v25, 16, 1
	v_lshrrev_b32_e32 v24, 16, v24
	v_add3_u32 v25, v25, v28, s16
	s_waitcnt lgkmcnt(0)
	v_add_f32_e32 v32, v32, v33
	v_and_or_b32 v24, v25, s17, v24
	v_bfe_u32 v25, v26, 16, 1
	ds_bpermute_b32 v33, v133, v32
	v_add3_u32 v25, v26, v25, s16
	v_bfe_u32 v26, v27, 16, 1
	v_lshrrev_b32_e32 v25, 16, v25
	v_add3_u32 v26, v27, v26, s16
	v_and_or_b32 v25, v26, s17, v25
	global_store_dwordx2 v[34:35], v[24:25], off offset:512 nt
	v_bfe_u32 v24, v20, 16, 1
	v_add3_u32 v20, v20, v24, s16
	v_bfe_u32 v24, v21, 16, 1
	s_waitcnt lgkmcnt(0)
	v_add_f32_e32 v32, v32, v33
	v_lshrrev_b32_e32 v20, 16, v20
	v_add3_u32 v21, v21, v24, s16
	ds_bpermute_b32 v33, v135, v32
	v_and_or_b32 v20, v21, s17, v20
	v_bfe_u32 v21, v22, 16, 1
	v_add3_u32 v21, v22, v21, s16
	v_bfe_u32 v22, v23, 16, 1
	v_lshrrev_b32_e32 v21, 16, v21
	v_add3_u32 v22, v23, v22, s16
	v_and_or_b32 v21, v22, s17, v21
	global_store_dwordx2 v[34:35], v[20:21], off offset:1024 nt
	v_bfe_u32 v20, v16, 16, 1
	s_waitcnt lgkmcnt(0)
	v_add_f32_e32 v32, v32, v33
	v_add3_u32 v16, v16, v20, s16
	v_bfe_u32 v20, v17, 16, 1
	ds_bpermute_b32 v33, v134, v32
	v_lshrrev_b32_e32 v16, 16, v16
	v_add3_u32 v17, v17, v20, s16
	v_and_or_b32 v16, v17, s17, v16
	v_bfe_u32 v17, v18, 16, 1
	v_add3_u32 v17, v18, v17, s16
	v_bfe_u32 v18, v19, 16, 1
	v_lshrrev_b32_e32 v17, 16, v17
	v_add3_u32 v18, v19, v18, s16
	v_and_or_b32 v17, v18, s17, v17
	global_store_dwordx2 v[34:35], v[16:17], off offset:1536 nt
	s_and_saveexec_b64 s[10:11], s[0:1]
	v_readlane_b32 s71, v252, 13
	s_cbranch_execz .LBB0_137
	s_waitcnt lgkmcnt(0)
	v_add_f32_e32 v16, v32, v33
	v_mov_b32_e32 v17, 0x358637bd
	v_fmac_f32_e32 v17, 0x3a800000, v16
	s_mov_b32 s2, 0xf800000
	v_mul_f32_e32 v16, 0x4f800000, v17
	v_cmp_gt_f32_e32 vcc, s2, v17
	s_nop 1
	v_cndmask_b32_e32 v16, v17, v16, vcc
	v_sqrt_f32_e32 v17, v16
	s_nop 0
	v_add_u32_e32 v18, -1, v17
	v_fma_f32 v19, -v18, v17, v16
	v_cmp_ge_f32_e64 s[2:3], 0, v19
	v_add_u32_e32 v19, 1, v17
	s_nop 0
	v_cndmask_b32_e64 v18, v17, v18, s[2:3]
	v_fma_f32 v17, -v19, v17, v16
	v_cmp_lt_f32_e64 s[2:3], 0, v17
	s_nop 1
	v_cndmask_b32_e64 v17, v18, v19, s[2:3]
	v_mul_f32_e32 v18, 0x37800000, v17
	v_cndmask_b32_e32 v17, v17, v18, vcc
	v_mov_b32_e32 v18, 0x260
	v_cmp_class_f32_e32 vcc, v16, v18
	s_nop 1
	v_cndmask_b32_e32 v16, v17, v16, vcc
	v_div_scale_f32 v17, s[2:3], v16, v16, 1.0
	v_rcp_f32_e32 v18, v17
	s_lshl_b64 s[2:3], s[74:75], 2
	s_add_u32 s2, s14, s2
	s_addc_u32 s3, s15, s3
	v_fma_f32 v19, -v17, v18, 1.0
	v_fmac_f32_e32 v18, v19, v18
	v_div_scale_f32 v19, vcc, 1.0, v16, 1.0
	v_mul_f32_e32 v20, v19, v18
	v_fma_f32 v21, -v17, v20, v19
	v_fmac_f32_e32 v20, v21, v18
	v_fma_f32 v17, -v17, v20, v19
	v_div_fmas_f32 v17, v17, v18, v20
	v_div_fixup_f32 v16, v17, v16, 1.0
	v_mov_b32_e32 v17, 0
	global_store_dword v17, v16, s[2:3]
.LBB0_137:
	s_or_b64 exec, exec, s[10:11]
	s_waitcnt vmcnt(31)
	v_mul_f32_e32 v16, v13, v13
	v_mul_f32_e32 v17, v15, v15
	v_fmac_f32_e32 v16, v12, v12
	v_fmac_f32_e32 v17, v14, v14
	v_add_f32_e32 v16, v16, v17
	s_waitcnt vmcnt(30)
	v_mul_f32_e32 v17, v9, v9
	v_mul_f32_e32 v18, v11, v11
	v_fmac_f32_e32 v17, v8, v8
	v_fmac_f32_e32 v18, v10, v10
	v_add_f32_e32 v17, v17, v18
	v_add_f32_e32 v16, v16, v17
	s_waitcnt vmcnt(29)
	v_mul_f32_e32 v17, v5, v5
	v_mul_f32_e32 v18, v7, v7
	v_fmac_f32_e32 v17, v4, v4
	v_fmac_f32_e32 v18, v6, v6
	v_add_f32_e32 v17, v17, v18
	v_add_f32_e32 v16, v16, v17
	s_waitcnt vmcnt(28)
	v_mul_f32_e32 v17, v1, v1
	v_mul_f32_e32 v18, v3, v3
	v_fmac_f32_e32 v17, v0, v0
	v_fmac_f32_e32 v18, v2, v2
	v_add_f32_e32 v17, v17, v18
	v_add_f32_e32 v16, v16, v17
	ds_bpermute_b32 v17, v130, v16
	v_bfe_u32 v20, v12, 16, 1
	v_add3_u32 v12, v12, v20, s16
	v_bfe_u32 v20, v13, 16, 1
	v_lshrrev_b32_e32 v12, 16, v12
	s_waitcnt lgkmcnt(0)
	v_add_f32_e32 v16, v16, v17
	ds_bpermute_b32 v17, v131, v16
	v_add3_u32 v13, v13, v20, s16
	s_lshl_b64 s[2:3], s[72:73], 11
	v_and_or_b32 v12, v13, s17, v12
	v_bfe_u32 v13, v14, 16, 1
	s_waitcnt lgkmcnt(0)
	v_add_f32_e32 v16, v16, v17
	s_add_u32 s2, s20, s2
	v_add3_u32 v13, v14, v13, s16
	v_bfe_u32 v14, v15, 16, 1
	ds_bpermute_b32 v17, v132, v16
	s_addc_u32 s3, s21, s3
	v_lshrrev_b32_e32 v13, 16, v13
	v_add3_u32 v14, v15, v14, s16
	v_lshl_add_u64 v[18:19], v[128:129], 3, s[2:3]
	v_and_or_b32 v13, v14, s17, v13
	global_store_dwordx2 v[18:19], v[12:13], off nt
	v_bfe_u32 v12, v8, 16, 1
	v_add3_u32 v8, v8, v12, s16
	v_bfe_u32 v12, v9, 16, 1
	v_lshrrev_b32_e32 v8, 16, v8
	v_add3_u32 v9, v9, v12, s16
	s_waitcnt lgkmcnt(0)
	v_add_f32_e32 v16, v16, v17
	v_and_or_b32 v8, v9, s17, v8
	v_bfe_u32 v9, v10, 16, 1
	ds_bpermute_b32 v17, v133, v16
	v_add3_u32 v9, v10, v9, s16
	v_bfe_u32 v10, v11, 16, 1
	v_lshrrev_b32_e32 v9, 16, v9
	v_add3_u32 v10, v11, v10, s16
	v_and_or_b32 v9, v10, s17, v9
	global_store_dwordx2 v[18:19], v[8:9], off offset:512 nt
	v_bfe_u32 v8, v4, 16, 1
	v_add3_u32 v4, v4, v8, s16
	v_bfe_u32 v8, v5, 16, 1
	s_waitcnt lgkmcnt(0)
	v_add_f32_e32 v16, v16, v17
	v_lshrrev_b32_e32 v4, 16, v4
	v_add3_u32 v5, v5, v8, s16
	ds_bpermute_b32 v17, v135, v16
	v_and_or_b32 v4, v5, s17, v4
	v_bfe_u32 v5, v6, 16, 1
	v_add3_u32 v5, v6, v5, s16
	v_bfe_u32 v6, v7, 16, 1
	v_lshrrev_b32_e32 v5, 16, v5
	v_add3_u32 v6, v7, v6, s16
	v_and_or_b32 v5, v6, s17, v5
	global_store_dwordx2 v[18:19], v[4:5], off offset:1024 nt
	v_bfe_u32 v4, v0, 16, 1
	s_waitcnt lgkmcnt(0)
	v_add_f32_e32 v16, v16, v17
	v_add3_u32 v0, v0, v4, s16
	v_bfe_u32 v4, v1, 16, 1
	ds_bpermute_b32 v17, v134, v16
	v_lshrrev_b32_e32 v0, 16, v0
	v_add3_u32 v1, v1, v4, s16
	v_and_or_b32 v0, v1, s17, v0
	v_bfe_u32 v1, v2, 16, 1
	v_add3_u32 v1, v2, v1, s16
	v_bfe_u32 v2, v3, 16, 1
	v_lshrrev_b32_e32 v1, 16, v1
	v_add3_u32 v2, v3, v2, s16
	v_and_or_b32 v1, v2, s17, v1
	global_store_dwordx2 v[18:19], v[0:1], off offset:1536 nt
	s_and_saveexec_b64 s[10:11], s[0:1]
	s_cbranch_execz .LBB0_139
	s_waitcnt lgkmcnt(0)
	v_add_f32_e32 v0, v16, v17
	v_mov_b32_e32 v1, 0x358637bd
	v_fmac_f32_e32 v1, 0x3a800000, v0
	s_mov_b32 s2, 0xf800000
	v_mul_f32_e32 v0, 0x4f800000, v1
	v_cmp_gt_f32_e32 vcc, s2, v1
	s_nop 1
	v_cndmask_b32_e32 v0, v1, v0, vcc
	v_sqrt_f32_e32 v1, v0
	s_nop 0
	v_add_u32_e32 v2, -1, v1
	v_fma_f32 v3, -v2, v1, v0
	v_cmp_ge_f32_e64 s[2:3], 0, v3
	v_add_u32_e32 v3, 1, v1
	s_nop 0
	v_cndmask_b32_e64 v2, v1, v2, s[2:3]
	v_fma_f32 v1, -v3, v1, v0
	v_cmp_lt_f32_e64 s[2:3], 0, v1
	s_nop 1
	v_cndmask_b32_e64 v1, v2, v3, s[2:3]
	v_mul_f32_e32 v2, 0x37800000, v1
	v_cndmask_b32_e32 v1, v1, v2, vcc
	v_mov_b32_e32 v2, 0x260
	v_cmp_class_f32_e32 vcc, v0, v2
	s_nop 1
	v_cndmask_b32_e32 v0, v1, v0, vcc
	v_div_scale_f32 v1, s[2:3], v0, v0, 1.0
	v_rcp_f32_e32 v2, v1
	s_lshl_b64 s[2:3], s[72:73], 2
	s_add_u32 s2, s14, s2
	s_addc_u32 s3, s15, s3
	v_fma_f32 v3, -v1, v2, 1.0
	v_fmac_f32_e32 v2, v3, v2
	v_div_scale_f32 v3, vcc, 1.0, v0, 1.0
	v_mul_f32_e32 v4, v3, v2
	v_fma_f32 v5, -v1, v4, v3
	v_fmac_f32_e32 v4, v5, v2
	v_fma_f32 v1, -v1, v4, v3
	v_div_fmas_f32 v1, v1, v2, v4
	v_div_fixup_f32 v0, v1, v0, 1.0
	v_mov_b32_e32 v1, 0
	global_store_dword v1, v0, s[2:3]
.LBB0_139:
	s_or_b64 exec, exec, s[10:11]
	s_waitcnt vmcnt(31)
	v_mul_f32_e32 v0, v125, v125
	v_mul_f32_e32 v1, v127, v127
	v_fmac_f32_e32 v0, v124, v124
	v_fmac_f32_e32 v1, v126, v126
	v_add_f32_e32 v0, v0, v1
	s_waitcnt vmcnt(30)
	v_mul_f32_e32 v1, v121, v121
	v_mul_f32_e32 v2, v123, v123
	v_fmac_f32_e32 v1, v120, v120
	v_fmac_f32_e32 v2, v122, v122
	v_add_f32_e32 v1, v1, v2
	v_add_f32_e32 v0, v0, v1
	s_waitcnt vmcnt(29)
	v_mul_f32_e32 v1, v117, v117
	v_mul_f32_e32 v2, v119, v119
	v_fmac_f32_e32 v1, v116, v116
	v_fmac_f32_e32 v2, v118, v118
	v_add_f32_e32 v1, v1, v2
	v_add_f32_e32 v0, v0, v1
	s_waitcnt vmcnt(28)
	v_mul_f32_e32 v1, v113, v113
	v_mul_f32_e32 v2, v115, v115
	v_fmac_f32_e32 v1, v112, v112
	v_fmac_f32_e32 v2, v114, v114
	v_add_f32_e32 v1, v1, v2
	v_add_f32_e32 v0, v0, v1
	ds_bpermute_b32 v1, v130, v0
	v_bfe_u32 v4, v124, 16, 1
	v_add3_u32 v4, v124, v4, s16
	v_bfe_u32 v5, v125, 16, 1
	v_lshrrev_b32_e32 v4, 16, v4
	s_waitcnt lgkmcnt(0)
	v_add_f32_e32 v0, v0, v1
	ds_bpermute_b32 v1, v131, v0
	v_add3_u32 v5, v125, v5, s16
	s_lshl_b64 s[2:3], s[6:7], 11
	v_and_or_b32 v4, v5, s17, v4
	v_bfe_u32 v5, v126, 16, 1
	s_waitcnt lgkmcnt(0)
	v_add_f32_e32 v0, v0, v1
	s_add_u32 s2, s20, s2
	v_add3_u32 v5, v126, v5, s16
	v_bfe_u32 v6, v127, 16, 1
	ds_bpermute_b32 v1, v132, v0
	s_addc_u32 s3, s21, s3
	v_lshrrev_b32_e32 v5, 16, v5
	v_add3_u32 v6, v127, v6, s16
	v_lshl_add_u64 v[2:3], v[128:129], 3, s[2:3]
	v_and_or_b32 v5, v6, s17, v5
	global_store_dwordx2 v[2:3], v[4:5], off nt
	v_bfe_u32 v4, v120, 16, 1
	v_add3_u32 v4, v120, v4, s16
	v_bfe_u32 v5, v121, 16, 1
	v_lshrrev_b32_e32 v4, 16, v4
	v_add3_u32 v5, v121, v5, s16
	s_waitcnt lgkmcnt(0)
	v_add_f32_e32 v0, v0, v1
	v_and_or_b32 v4, v5, s17, v4
	v_bfe_u32 v5, v122, 16, 1
	ds_bpermute_b32 v1, v133, v0
	v_add3_u32 v5, v122, v5, s16
	v_bfe_u32 v6, v123, 16, 1
	v_lshrrev_b32_e32 v5, 16, v5
	v_add3_u32 v6, v123, v6, s16
	v_and_or_b32 v5, v6, s17, v5
	global_store_dwordx2 v[2:3], v[4:5], off offset:512 nt
	v_bfe_u32 v4, v116, 16, 1
	v_add3_u32 v4, v116, v4, s16
	v_bfe_u32 v5, v117, 16, 1
	s_waitcnt lgkmcnt(0)
	v_add_f32_e32 v0, v0, v1
	v_lshrrev_b32_e32 v4, 16, v4
	v_add3_u32 v5, v117, v5, s16
	ds_bpermute_b32 v1, v135, v0
	v_and_or_b32 v4, v5, s17, v4
	v_bfe_u32 v5, v118, 16, 1
	v_add3_u32 v5, v118, v5, s16
	v_bfe_u32 v6, v119, 16, 1
	v_lshrrev_b32_e32 v5, 16, v5
	v_add3_u32 v6, v119, v6, s16
	v_and_or_b32 v5, v6, s17, v5
	global_store_dwordx2 v[2:3], v[4:5], off offset:1024 nt
	v_bfe_u32 v4, v112, 16, 1
	s_waitcnt lgkmcnt(0)
	v_add_f32_e32 v0, v0, v1
	v_add3_u32 v4, v112, v4, s16
	v_bfe_u32 v5, v113, 16, 1
	ds_bpermute_b32 v1, v134, v0
	v_lshrrev_b32_e32 v4, 16, v4
	v_add3_u32 v5, v113, v5, s16
	v_and_or_b32 v4, v5, s17, v4
	v_bfe_u32 v5, v114, 16, 1
	v_add3_u32 v5, v114, v5, s16
	v_bfe_u32 v6, v115, 16, 1
	v_lshrrev_b32_e32 v5, 16, v5
	v_add3_u32 v6, v115, v6, s16
	v_and_or_b32 v5, v6, s17, v5
	global_store_dwordx2 v[2:3], v[4:5], off offset:1536 nt
	s_and_saveexec_b64 s[10:11], s[0:1]
	s_cbranch_execz .LBB0_141
	s_waitcnt lgkmcnt(0)
	v_add_f32_e32 v0, v0, v1
	v_mov_b32_e32 v1, 0x358637bd
	v_fmac_f32_e32 v1, 0x3a800000, v0
	s_mov_b32 s2, 0xf800000
	v_mul_f32_e32 v0, 0x4f800000, v1
	v_cmp_gt_f32_e32 vcc, s2, v1
	s_nop 1
	v_cndmask_b32_e32 v0, v1, v0, vcc
	v_sqrt_f32_e32 v1, v0
	s_nop 0
	v_add_u32_e32 v2, -1, v1
	v_fma_f32 v3, -v2, v1, v0
	v_cmp_ge_f32_e64 s[2:3], 0, v3
	v_add_u32_e32 v3, 1, v1
	s_nop 0
	v_cndmask_b32_e64 v2, v1, v2, s[2:3]
	v_fma_f32 v1, -v3, v1, v0
	v_cmp_lt_f32_e64 s[2:3], 0, v1
	s_nop 1
	v_cndmask_b32_e64 v1, v2, v3, s[2:3]
	v_mul_f32_e32 v2, 0x37800000, v1
	v_cndmask_b32_e32 v1, v1, v2, vcc
	v_mov_b32_e32 v2, 0x260
	v_cmp_class_f32_e32 vcc, v0, v2
	s_nop 1
	v_cndmask_b32_e32 v0, v1, v0, vcc
	v_div_scale_f32 v1, s[2:3], v0, v0, 1.0
	v_rcp_f32_e32 v2, v1
	s_lshl_b64 s[2:3], s[6:7], 2
	s_add_u32 s2, s14, s2
	s_addc_u32 s3, s15, s3
	v_fma_f32 v3, -v1, v2, 1.0
	v_fmac_f32_e32 v2, v3, v2
	v_div_scale_f32 v3, vcc, 1.0, v0, 1.0
	v_mul_f32_e32 v4, v3, v2
	v_fma_f32 v5, -v1, v4, v3
	v_fmac_f32_e32 v4, v5, v2
	v_fma_f32 v1, -v1, v4, v3
	v_div_fmas_f32 v1, v1, v2, v4
	v_div_fixup_f32 v0, v1, v0, 1.0
	v_mov_b32_e32 v1, 0
	global_store_dword v1, v0, s[2:3]
.LBB0_141:
	s_or_b64 exec, exec, s[10:11]
	s_waitcnt vmcnt(31)
	v_mul_f32_e32 v0, v109, v109
	s_waitcnt lgkmcnt(0)
	v_mul_f32_e32 v1, v111, v111
	v_fmac_f32_e32 v0, v108, v108
	v_fmac_f32_e32 v1, v110, v110
	v_add_f32_e32 v0, v0, v1
	s_waitcnt vmcnt(30)
	v_mul_f32_e32 v1, v105, v105
	v_mul_f32_e32 v2, v107, v107
	v_fmac_f32_e32 v1, v104, v104
	v_fmac_f32_e32 v2, v106, v106
	v_add_f32_e32 v1, v1, v2
	v_add_f32_e32 v0, v0, v1
	s_waitcnt vmcnt(29)
	v_mul_f32_e32 v1, v101, v101
	v_mul_f32_e32 v2, v103, v103
	v_fmac_f32_e32 v1, v100, v100
	v_fmac_f32_e32 v2, v102, v102
	v_add_f32_e32 v1, v1, v2
	v_add_f32_e32 v0, v0, v1
	s_waitcnt vmcnt(28)
	v_mul_f32_e32 v1, v97, v97
	v_mul_f32_e32 v2, v99, v99
	v_fmac_f32_e32 v1, v96, v96
	v_fmac_f32_e32 v2, v98, v98
	v_add_f32_e32 v1, v1, v2
	v_add_f32_e32 v0, v0, v1
	ds_bpermute_b32 v1, v130, v0
	v_bfe_u32 v4, v108, 16, 1
	v_add3_u32 v4, v108, v4, s16
	v_bfe_u32 v5, v109, 16, 1
	v_lshrrev_b32_e32 v4, 16, v4
	s_waitcnt lgkmcnt(0)
	v_add_f32_e32 v0, v0, v1
	ds_bpermute_b32 v1, v131, v0
	v_add3_u32 v5, v109, v5, s16
	s_lshl_b64 s[2:3], s[8:9], 11
	v_and_or_b32 v4, v5, s17, v4
	v_bfe_u32 v5, v110, 16, 1
	s_waitcnt lgkmcnt(0)
	v_add_f32_e32 v0, v0, v1
	s_add_u32 s2, s20, s2
	v_add3_u32 v5, v110, v5, s16
	v_bfe_u32 v6, v111, 16, 1
	ds_bpermute_b32 v1, v132, v0
	s_addc_u32 s3, s21, s3
	v_lshrrev_b32_e32 v5, 16, v5
	v_add3_u32 v6, v111, v6, s16
	v_lshl_add_u64 v[2:3], v[128:129], 3, s[2:3]
	v_and_or_b32 v5, v6, s17, v5
	global_store_dwordx2 v[2:3], v[4:5], off nt
	v_bfe_u32 v4, v104, 16, 1
	v_add3_u32 v4, v104, v4, s16
	v_bfe_u32 v5, v105, 16, 1
	v_lshrrev_b32_e32 v4, 16, v4
	v_add3_u32 v5, v105, v5, s16
	s_waitcnt lgkmcnt(0)
	v_add_f32_e32 v0, v0, v1
	v_and_or_b32 v4, v5, s17, v4
	v_bfe_u32 v5, v106, 16, 1
	ds_bpermute_b32 v1, v133, v0
	v_add3_u32 v5, v106, v5, s16
	v_bfe_u32 v6, v107, 16, 1
	v_lshrrev_b32_e32 v5, 16, v5
	v_add3_u32 v6, v107, v6, s16
	v_and_or_b32 v5, v6, s17, v5
	global_store_dwordx2 v[2:3], v[4:5], off offset:512 nt
	v_bfe_u32 v4, v100, 16, 1
	v_add3_u32 v4, v100, v4, s16
	v_bfe_u32 v5, v101, 16, 1
	s_waitcnt lgkmcnt(0)
	v_add_f32_e32 v0, v0, v1
	v_lshrrev_b32_e32 v4, 16, v4
	v_add3_u32 v5, v101, v5, s16
	ds_bpermute_b32 v1, v135, v0
	v_and_or_b32 v4, v5, s17, v4
	v_bfe_u32 v5, v102, 16, 1
	v_add3_u32 v5, v102, v5, s16
	v_bfe_u32 v6, v103, 16, 1
	v_lshrrev_b32_e32 v5, 16, v5
	v_add3_u32 v6, v103, v6, s16
	v_and_or_b32 v5, v6, s17, v5
	global_store_dwordx2 v[2:3], v[4:5], off offset:1024 nt
	v_bfe_u32 v4, v96, 16, 1
	s_waitcnt lgkmcnt(0)
	v_add_f32_e32 v0, v0, v1
	v_add3_u32 v4, v96, v4, s16
	v_bfe_u32 v5, v97, 16, 1
	ds_bpermute_b32 v1, v134, v0
	v_lshrrev_b32_e32 v4, 16, v4
	v_add3_u32 v5, v97, v5, s16
	v_and_or_b32 v4, v5, s17, v4
	v_bfe_u32 v5, v98, 16, 1
	v_add3_u32 v5, v98, v5, s16
	v_bfe_u32 v6, v99, 16, 1
	v_lshrrev_b32_e32 v5, 16, v5
	v_add3_u32 v6, v99, v6, s16
	v_and_or_b32 v5, v6, s17, v5
	global_store_dwordx2 v[2:3], v[4:5], off offset:1536 nt
	s_and_saveexec_b64 s[10:11], s[0:1]
	s_cbranch_execz .LBB0_143
	s_waitcnt lgkmcnt(0)
	v_add_f32_e32 v0, v0, v1
	v_mov_b32_e32 v1, 0x358637bd
	v_fmac_f32_e32 v1, 0x3a800000, v0
	s_mov_b32 s2, 0xf800000
	v_mul_f32_e32 v0, 0x4f800000, v1
	v_cmp_gt_f32_e32 vcc, s2, v1
	s_nop 1
	v_cndmask_b32_e32 v0, v1, v0, vcc
	v_sqrt_f32_e32 v1, v0
	s_nop 0
	v_add_u32_e32 v2, -1, v1
	v_fma_f32 v3, -v2, v1, v0
	v_cmp_ge_f32_e64 s[2:3], 0, v3
	v_add_u32_e32 v3, 1, v1
	s_nop 0
	v_cndmask_b32_e64 v2, v1, v2, s[2:3]
	v_fma_f32 v1, -v3, v1, v0
	v_cmp_lt_f32_e64 s[2:3], 0, v1
	s_nop 1
	v_cndmask_b32_e64 v1, v2, v3, s[2:3]
	v_mul_f32_e32 v2, 0x37800000, v1
	v_cndmask_b32_e32 v1, v1, v2, vcc
	v_mov_b32_e32 v2, 0x260
	v_cmp_class_f32_e32 vcc, v0, v2
	s_nop 1
	v_cndmask_b32_e32 v0, v1, v0, vcc
	v_div_scale_f32 v1, s[2:3], v0, v0, 1.0
	v_rcp_f32_e32 v2, v1
	s_lshl_b64 s[2:3], s[8:9], 2
	s_add_u32 s2, s14, s2
	s_addc_u32 s3, s15, s3
	v_fma_f32 v3, -v1, v2, 1.0
	v_fmac_f32_e32 v2, v3, v2
	v_div_scale_f32 v3, vcc, 1.0, v0, 1.0
	v_mul_f32_e32 v4, v3, v2
	v_fma_f32 v5, -v1, v4, v3
	v_fmac_f32_e32 v4, v5, v2
	v_fma_f32 v1, -v1, v4, v3
	v_div_fmas_f32 v1, v1, v2, v4
	v_div_fixup_f32 v0, v1, v0, 1.0
	v_mov_b32_e32 v1, 0
	global_store_dword v1, v0, s[2:3]
.LBB0_143:
	s_or_b64 exec, exec, s[10:11]
	s_waitcnt vmcnt(31)
	v_mul_f32_e32 v0, v93, v93
	s_waitcnt lgkmcnt(0)
	v_mul_f32_e32 v1, v95, v95
	v_fmac_f32_e32 v0, v92, v92
	v_fmac_f32_e32 v1, v94, v94
	v_add_f32_e32 v0, v0, v1
	s_waitcnt vmcnt(30)
	v_mul_f32_e32 v1, v89, v89
	v_mul_f32_e32 v2, v91, v91
	v_fmac_f32_e32 v1, v88, v88
	v_fmac_f32_e32 v2, v90, v90
	v_add_f32_e32 v1, v1, v2
	v_add_f32_e32 v0, v0, v1
	s_waitcnt vmcnt(29)
	v_mul_f32_e32 v1, v85, v85
	v_mul_f32_e32 v2, v87, v87
	v_fmac_f32_e32 v1, v84, v84
	v_fmac_f32_e32 v2, v86, v86
	v_add_f32_e32 v1, v1, v2
	v_add_f32_e32 v0, v0, v1
	s_waitcnt vmcnt(28)
	v_mul_f32_e32 v1, v81, v81
	v_mul_f32_e32 v2, v83, v83
	v_fmac_f32_e32 v1, v80, v80
	v_fmac_f32_e32 v2, v82, v82
	v_add_f32_e32 v1, v1, v2
	v_add_f32_e32 v0, v0, v1
	ds_bpermute_b32 v1, v130, v0
	v_bfe_u32 v4, v92, 16, 1
	s_movk_i32 s7, 0x7fff
	s_add_i32 s8, s6, s13
	v_add3_u32 v4, v92, v4, s7
	s_waitcnt lgkmcnt(0)
	v_add_f32_e32 v0, v0, v1
	ds_bpermute_b32 v1, v131, v0
	v_bfe_u32 v5, v93, 16, 1
	s_ashr_i32 s9, s8, 31
	v_lshrrev_b32_e32 v4, 16, v4
	v_add3_u32 v5, v93, v5, s7
	s_mov_b32 s13, 0xffff0000
	s_lshl_b64 s[2:3], s[8:9], 11
	v_and_or_b32 v4, v5, s13, v4
	v_bfe_u32 v5, v94, 16, 1
	s_waitcnt lgkmcnt(0)
	v_add_f32_e32 v0, v0, v1
	s_add_u32 s2, s20, s2
	v_add3_u32 v5, v94, v5, s7
	v_bfe_u32 v6, v95, 16, 1
	ds_bpermute_b32 v1, v132, v0
	s_addc_u32 s3, s21, s3
	v_lshrrev_b32_e32 v5, 16, v5
	v_add3_u32 v6, v95, v6, s7
	v_lshl_add_u64 v[2:3], v[128:129], 3, s[2:3]
	v_and_or_b32 v5, v6, s13, v5
	global_store_dwordx2 v[2:3], v[4:5], off nt
	v_bfe_u32 v4, v88, 16, 1
	v_add3_u32 v4, v88, v4, s7
	v_bfe_u32 v5, v89, 16, 1
	v_lshrrev_b32_e32 v4, 16, v4
	v_add3_u32 v5, v89, v5, s7
	s_waitcnt lgkmcnt(0)
	v_add_f32_e32 v0, v0, v1
	v_and_or_b32 v4, v5, s13, v4
	v_bfe_u32 v5, v90, 16, 1
	ds_bpermute_b32 v1, v133, v0
	v_add3_u32 v5, v90, v5, s7
	v_bfe_u32 v6, v91, 16, 1
	v_lshrrev_b32_e32 v5, 16, v5
	v_add3_u32 v6, v91, v6, s7
	v_and_or_b32 v5, v6, s13, v5
	global_store_dwordx2 v[2:3], v[4:5], off offset:512 nt
	v_bfe_u32 v4, v84, 16, 1
	v_add3_u32 v4, v84, v4, s7
	v_bfe_u32 v5, v85, 16, 1
	s_waitcnt lgkmcnt(0)
	v_add_f32_e32 v0, v0, v1
	v_lshrrev_b32_e32 v4, 16, v4
	v_add3_u32 v5, v85, v5, s7
	ds_bpermute_b32 v1, v135, v0
	v_and_or_b32 v4, v5, s13, v4
	v_bfe_u32 v5, v86, 16, 1
	v_add3_u32 v5, v86, v5, s7
	v_bfe_u32 v6, v87, 16, 1
	v_lshrrev_b32_e32 v5, 16, v5
	v_add3_u32 v6, v87, v6, s7
	v_and_or_b32 v5, v6, s13, v5
	global_store_dwordx2 v[2:3], v[4:5], off offset:1024 nt
	v_bfe_u32 v4, v80, 16, 1
	s_waitcnt lgkmcnt(0)
	v_add_f32_e32 v0, v0, v1
	v_add3_u32 v4, v80, v4, s7
	v_bfe_u32 v5, v81, 16, 1
	ds_bpermute_b32 v1, v134, v0
	v_lshrrev_b32_e32 v4, 16, v4
	v_add3_u32 v5, v81, v5, s7
	v_and_or_b32 v4, v5, s13, v4
	v_bfe_u32 v5, v82, 16, 1
	v_add3_u32 v5, v82, v5, s7
	v_bfe_u32 v6, v83, 16, 1
	v_lshrrev_b32_e32 v5, 16, v5
	v_add3_u32 v6, v83, v6, s7
	v_and_or_b32 v5, v6, s13, v5
	global_store_dwordx2 v[2:3], v[4:5], off offset:1536 nt
	s_and_saveexec_b64 s[10:11], s[0:1]
	s_cbranch_execz .LBB0_145
	s_waitcnt lgkmcnt(0)
	v_add_f32_e32 v0, v0, v1
	v_mov_b32_e32 v1, 0x358637bd
	v_fmac_f32_e32 v1, 0x3a800000, v0
	s_mov_b32 s2, 0xf800000
	v_mul_f32_e32 v0, 0x4f800000, v1
	v_cmp_gt_f32_e32 vcc, s2, v1
	s_nop 1
	v_cndmask_b32_e32 v0, v1, v0, vcc
	v_sqrt_f32_e32 v1, v0
	s_nop 0
	v_add_u32_e32 v2, -1, v1
	v_fma_f32 v3, -v2, v1, v0
	v_cmp_ge_f32_e64 s[2:3], 0, v3
	v_add_u32_e32 v3, 1, v1
	s_nop 0
	v_cndmask_b32_e64 v2, v1, v2, s[2:3]
	v_fma_f32 v1, -v3, v1, v0
	v_cmp_lt_f32_e64 s[2:3], 0, v1
	s_nop 1
	v_cndmask_b32_e64 v1, v2, v3, s[2:3]
	v_mul_f32_e32 v2, 0x37800000, v1
	v_cndmask_b32_e32 v1, v1, v2, vcc
	v_mov_b32_e32 v2, 0x260
	v_cmp_class_f32_e32 vcc, v0, v2
	s_nop 1
	v_cndmask_b32_e32 v0, v1, v0, vcc
	v_div_scale_f32 v1, s[2:3], v0, v0, 1.0
	v_rcp_f32_e32 v2, v1
	s_lshl_b64 s[2:3], s[8:9], 2
	s_add_u32 s2, s14, s2
	s_addc_u32 s3, s15, s3
	v_fma_f32 v3, -v1, v2, 1.0
	v_fmac_f32_e32 v2, v3, v2
	v_div_scale_f32 v3, vcc, 1.0, v0, 1.0
	v_mul_f32_e32 v4, v3, v2
	v_fma_f32 v5, -v1, v4, v3
	v_fmac_f32_e32 v4, v5, v2
	v_fma_f32 v1, -v1, v4, v3
	v_div_fmas_f32 v1, v1, v2, v4
	v_div_fixup_f32 v0, v1, v0, 1.0
	v_mov_b32_e32 v1, 0
	global_store_dword v1, v0, s[2:3]
.LBB0_145:
	s_or_b64 exec, exec, s[10:11]
	s_waitcnt vmcnt(31)
	v_mul_f32_e32 v0, v77, v77
	s_waitcnt lgkmcnt(0)
	v_mul_f32_e32 v1, v79, v79
	v_fmac_f32_e32 v0, v76, v76
	v_fmac_f32_e32 v1, v78, v78
	v_add_f32_e32 v0, v0, v1
	s_waitcnt vmcnt(30)
	v_mul_f32_e32 v1, v73, v73
	v_mul_f32_e32 v2, v75, v75
	v_fmac_f32_e32 v1, v72, v72
	v_fmac_f32_e32 v2, v74, v74
	v_add_f32_e32 v1, v1, v2
	v_add_f32_e32 v0, v0, v1
	s_waitcnt vmcnt(29)
	v_mul_f32_e32 v1, v69, v69
	v_mul_f32_e32 v2, v71, v71
	v_fmac_f32_e32 v1, v68, v68
	v_fmac_f32_e32 v2, v70, v70
	v_add_f32_e32 v1, v1, v2
	v_add_f32_e32 v0, v0, v1
	s_waitcnt vmcnt(28)
	v_mul_f32_e32 v1, v65, v65
	v_mul_f32_e32 v2, v67, v67
	v_fmac_f32_e32 v1, v64, v64
	v_fmac_f32_e32 v2, v66, v66
	v_add_f32_e32 v1, v1, v2
	v_add_f32_e32 v0, v0, v1
	ds_bpermute_b32 v1, v130, v0
	v_bfe_u32 v4, v76, 16, 1
	s_add_i32 s2, s6, s12
	v_add3_u32 v4, v76, v4, s7
	v_bfe_u32 v5, v77, 16, 1
	s_waitcnt lgkmcnt(0)
	v_add_f32_e32 v0, v0, v1
	ds_bpermute_b32 v1, v131, v0
	s_ashr_i32 s3, s2, 31
	v_lshrrev_b32_e32 v4, 16, v4
	v_add3_u32 v5, v77, v5, s7
	s_lshl_b64 s[8:9], s[2:3], 11
	v_and_or_b32 v4, v5, s13, v4
	v_bfe_u32 v5, v78, 16, 1
	s_waitcnt lgkmcnt(0)
	v_add_f32_e32 v0, v0, v1
	s_add_u32 s8, s20, s8
	v_add3_u32 v5, v78, v5, s7
	v_bfe_u32 v6, v79, 16, 1
	ds_bpermute_b32 v1, v132, v0
	s_addc_u32 s9, s21, s9
	v_lshrrev_b32_e32 v5, 16, v5
	v_add3_u32 v6, v79, v6, s7
	v_lshl_add_u64 v[2:3], v[128:129], 3, s[8:9]
	v_and_or_b32 v5, v6, s13, v5
	global_store_dwordx2 v[2:3], v[4:5], off nt
	v_bfe_u32 v4, v72, 16, 1
	v_add3_u32 v4, v72, v4, s7
	v_bfe_u32 v5, v73, 16, 1
	v_lshrrev_b32_e32 v4, 16, v4
	v_add3_u32 v5, v73, v5, s7
	s_waitcnt lgkmcnt(0)
	v_add_f32_e32 v0, v0, v1
	v_and_or_b32 v4, v5, s13, v4
	v_bfe_u32 v5, v74, 16, 1
	ds_bpermute_b32 v1, v133, v0
	v_add3_u32 v5, v74, v5, s7
	v_bfe_u32 v6, v75, 16, 1
	v_lshrrev_b32_e32 v5, 16, v5
	v_add3_u32 v6, v75, v6, s7
	v_and_or_b32 v5, v6, s13, v5
	global_store_dwordx2 v[2:3], v[4:5], off offset:512 nt
	v_bfe_u32 v4, v68, 16, 1
	v_add3_u32 v4, v68, v4, s7
	v_bfe_u32 v5, v69, 16, 1
	s_waitcnt lgkmcnt(0)
	v_add_f32_e32 v0, v0, v1
	v_lshrrev_b32_e32 v4, 16, v4
	v_add3_u32 v5, v69, v5, s7
	ds_bpermute_b32 v1, v135, v0
	v_and_or_b32 v4, v5, s13, v4
	v_bfe_u32 v5, v70, 16, 1
	v_add3_u32 v5, v70, v5, s7
	v_bfe_u32 v6, v71, 16, 1
	v_lshrrev_b32_e32 v5, 16, v5
	v_add3_u32 v6, v71, v6, s7
	v_and_or_b32 v5, v6, s13, v5
	global_store_dwordx2 v[2:3], v[4:5], off offset:1024 nt
	v_bfe_u32 v4, v64, 16, 1
	s_waitcnt lgkmcnt(0)
	v_add_f32_e32 v0, v0, v1
	v_add3_u32 v4, v64, v4, s7
	v_bfe_u32 v5, v65, 16, 1
	ds_bpermute_b32 v1, v134, v0
	v_lshrrev_b32_e32 v4, 16, v4
	v_add3_u32 v5, v65, v5, s7
	v_and_or_b32 v4, v5, s13, v4
	v_bfe_u32 v5, v66, 16, 1
	v_add3_u32 v5, v66, v5, s7
	v_bfe_u32 v6, v67, 16, 1
	v_lshrrev_b32_e32 v5, 16, v5
	v_add3_u32 v6, v67, v6, s7
	v_and_or_b32 v5, v6, s13, v5
	global_store_dwordx2 v[2:3], v[4:5], off offset:1536 nt
	s_and_saveexec_b64 s[6:7], s[0:1]
	s_cbranch_execz .LBB0_147
	s_waitcnt lgkmcnt(0)
	v_add_f32_e32 v0, v0, v1
	v_mov_b32_e32 v1, 0x358637bd
	v_fmac_f32_e32 v1, 0x3a800000, v0
	s_mov_b32 s0, 0xf800000
	v_mul_f32_e32 v0, 0x4f800000, v1
	v_cmp_gt_f32_e32 vcc, s0, v1
	s_nop 1
	v_cndmask_b32_e32 v0, v1, v0, vcc
	v_sqrt_f32_e32 v1, v0
	s_nop 0
	v_add_u32_e32 v2, -1, v1
	v_fma_f32 v3, -v2, v1, v0
	v_cmp_ge_f32_e64 s[0:1], 0, v3
	v_add_u32_e32 v3, 1, v1
	s_nop 0
	v_cndmask_b32_e64 v2, v1, v2, s[0:1]
	v_fma_f32 v1, -v3, v1, v0
	v_cmp_lt_f32_e64 s[0:1], 0, v1
	s_nop 1
	v_cndmask_b32_e64 v1, v2, v3, s[0:1]
	v_mul_f32_e32 v2, 0x37800000, v1
	v_cndmask_b32_e32 v1, v1, v2, vcc
	v_mov_b32_e32 v2, 0x260
	v_cmp_class_f32_e32 vcc, v0, v2
	s_nop 1
	v_cndmask_b32_e32 v0, v1, v0, vcc
	v_div_scale_f32 v1, s[0:1], v0, v0, 1.0
	v_rcp_f32_e32 v2, v1
	s_lshl_b64 s[0:1], s[2:3], 2
	s_add_u32 s0, s14, s0
	s_addc_u32 s1, s15, s1
	v_fma_f32 v3, -v1, v2, 1.0
	v_fmac_f32_e32 v2, v3, v2
	v_div_scale_f32 v3, vcc, 1.0, v0, 1.0
	v_mul_f32_e32 v4, v3, v2
	v_fma_f32 v5, -v1, v4, v3
	v_fmac_f32_e32 v4, v5, v2
	v_fma_f32 v1, -v1, v4, v3
	v_div_fmas_f32 v1, v1, v2, v4
	v_div_fixup_f32 v0, v1, v0, 1.0
	v_mov_b32_e32 v1, 0
	global_store_dword v1, v0, s[0:1]
